# 12c: per-group expert-id and weight rows loaded once (dwordx2 per lane) and rebuilt by DPP moves instead of 8 broadcast dwordx4 loads; 32-bit gather offsets
# baseline (speedup 1.0000x reference)
; DI void peer_v_phase(const Params& p) {
;     ...
;   const int g = blockIdx.x & 7, rank = blockIdx.x >> 3, nrank = gridDim.x >> 3;
;   if (rank >= nrank) return;
;   const int q = lane >> 3, s = lane & 7;
;   const unsigned char* Vb = (const unsigned char*)(p.ws + OFF_VB) + (size_t)g * (16384 * 128) + 16 * s;
;   const int* EID = (const int*)(p.ws + OFF_EID);
;   const float* W = (const float*)(p.ws + OFF_W);
;   float* SSP = (float*)(p.ws + OFF_SSP) + (size_t)g * T_TOK;
;   const int first = rank * 4 + wave, stride = nrank * 4;
;   const int n = (T_TOK - first + stride - 1) / stride;
;   auto tokof = [&](int k) { return first + (k < n ? k : n - 1) * stride; };
;   auto gather = [&](PeerVRows& r, const int* e, int tok) {
; #pragma unroll
;     for (int i = 0; i < 16; ++i) r.v[i] = *(const u32x4*)(Vb + (size_t)e[i] * 128);
;     const float4* wp = (const float4*)(W + (size_t)tok * 128 + 16 * q);
; #pragma unroll
;     for (int j = 0; j < 4; ++j) r.w[j] = wp[j];
;   };
;     ...
;   int ea[16], eb[16];
;   PeerVRows ga, gb;
;   peer_load_e(ea, EID, tokof(0), q);
;   peer_load_e(eb, EID, tokof(1), q);
;   gather(ga, ea, tokof(0));
.LBB0_1473:
	s_or_b64 exec, exec, s[4:5]
	v_mov_b32_e32 v62, v192
	s_andn2_b64 vcc, exec, s[10:11]
	s_waitcnt lgkmcnt(0)
	s_barrier
	s_cbranch_vccnz .LBB0_1483
	s_lshl_b32 s18, s0, 2
	v_cvt_f32_u32_e32 v0, s18
	v_ashrrev_i32_e32 v1, 6, v62
	v_lshl_add_u32 v194, s1, 2, v1
	v_sub_u32_e32 v1, s18, v194
	v_rcp_iflag_f32_e32 v0, v0
	v_add_u32_e32 v1, 0x3fff, v1
	s_sub_i32 s1, 0, s18
	v_sub_u32_e32 v3, 0, v1
	v_mul_f32_e32 v0, 0x4f7ffffe, v0
	v_cvt_u32_f32_e32 v0, v0
	v_ashrrev_i32_e32 v2, 31, v1
	v_max_i32_e32 v1, v1, v3
	v_mul_lo_u32 v3, s1, v0
	v_mul_hi_u32 v3, v0, v3
	v_add_u32_e32 v0, v0, v3
	v_mul_hi_u32 v0, v1, v0
	v_mul_lo_u32 v3, v0, s18
	v_sub_u32_e32 v1, v1, v3
	v_add_u32_e32 v4, 1, v0
	v_cmp_le_u32_e32 vcc, s18, v1
	v_subrev_u32_e32 v3, s18, v1
	s_nop 0
	v_cndmask_b32_e32 v0, v0, v4, vcc
	v_cndmask_b32_e32 v1, v1, v3, vcc
	v_add_u32_e32 v3, 1, v0
	v_cmp_le_u32_e32 vcc, s18, v1
	s_nop 1
	v_cndmask_b32_e32 v0, v0, v3, vcc
	v_xor_b32_e32 v0, v0, v2
	v_sub_u32_e32 v193, v0, v2
	v_cmp_lt_i32_e32 vcc, 0, v193
	s_and_saveexec_b64 s[10:11], vcc
	s_cbranch_execz .LBB0_1482
	v_lshlrev_b32_e32 v0, 3, v62
	v_ashrrev_i32_e32 v195, 31, v194
	v_mov_b32_e32 v61, 0
	v_and_b32_e32 v72, 0x1c0, v0
	v_lshlrev_b64 v[0:1], 9, v[194:195]
	v_mov_b32_e32 v73, v61
	v_lshl_add_u64 v[2:3], s[86:87], 0, v[0:1]
	v_lshl_add_u64 v[2:3], v[2:3], 0, v[72:73]
	global_load_dwordx4 v[4:7], v[2:3], off offset:48
	global_load_dwordx4 v[8:11], v[2:3], off offset:32
	global_load_dwordx4 v[16:19], v[2:3], off offset:16
	global_load_dwordx4 v[68:71], v[2:3], off
	s_and_b32 s8, s80, 7
	s_lshl_b32 s1, s8, 21
	v_lshlrev_b32_e32 v2, 4, v62
	s_add_u32 s2, s86, s1
	v_and_b32_e32 v60, 0x70, v2
	v_mov_b32_e32 v231, v60
	s_addc_u32 s3, s87, 0
	s_add_u32 s100, s2, 0x9000000
	s_addc_u32 s101, s3, 0
	v_lshl_add_u64 v[2:3], s[2:3], 0, v[60:61]
	s_add_u32 s2, s86, 0x5000000
	s_addc_u32 s3, s87, 0
	v_lshl_add_u64 v[0:1], s[2:3], 0, v[0:1]
	s_mov_b64 s[4:5], 0x9000000
	v_lshl_add_u64 v[20:21], v[0:1], 0, v[72:73]
	v_lshl_add_u64 v[196:197], v[2:3], 0, s[4:5]
	v_and_b32_e32 v232, 7, v192
	v_lshlrev_b32_e32 v232, 3, v232
	v_mov_b32_e32 v233, 0
	v_lshl_add_u64 v[234:235], v[20:21], 0, v[232:233]
	global_load_dwordx2 v[242:243], v[234:235], off
	v_add_u32_e32 v195, -1, v193
	v_mov_b32_e32 v63, s18
	v_cmp_ne_u32_e32 vcc, 0, v195
	s_lshl_b32 s1, s8, 16
	v_lshl_add_u64 v[200:201], s[2:3], 0, v[72:73]
	v_cndmask_b32_e32 v63, 0, v63, vcc
	s_add_u32 s1, s86, s1
	s_addc_u32 s4, s87, 0
	s_add_u32 s12, s1, 0x5800000
	s_addc_u32 s13, s4, 0
	s_lshl_b32 s8, s8, 9
	s_add_u32 s8, s84, s8
	s_addc_u32 s9, s85, 0
	v_lshlrev_b32_e32 v60, 2, v60
	s_mov_b32 s1, 3
	v_lshl_add_u64 v[198:199], s[86:87], 0, v[72:73]
	s_lshl_b32 s0, s0, 3
	s_mov_b64 s[14:15], 0
	v_mov_b32_e32 v204, v194
	s_waitcnt vmcnt(4)
	v_mov_b32_e32 v20, v7
	v_mov_b32_e32 v22, v5
	s_waitcnt vmcnt(1)
	v_mov_b32_e32 v74, v71
	v_mov_b32_e32 v24, v11
	v_mov_b32_e32 v26, v9
	v_mov_b32_e32 v32, v19
	v_mov_b32_e32 v34, v17
	v_lshlrev_b32_e32 v6, 7, v6
	v_lshlrev_b32_e32 v20, 7, v20
	v_lshlrev_b32_e32 v4, 7, v4
	v_lshlrev_b32_e32 v22, 7, v22
	v_lshlrev_b32_e32 v70, 7, v70
	v_lshlrev_b32_e32 v74, 7, v74
	v_lshlrev_b32_e32 v10, 7, v10
	v_lshlrev_b32_e32 v24, 7, v24
	v_lshlrev_b32_e32 v8, 7, v8
	v_lshlrev_b32_e32 v26, 7, v26
	v_lshlrev_b32_e32 v18, 7, v18
	v_lshlrev_b32_e32 v32, 7, v32
	v_lshlrev_b32_e32 v16, 7, v16
	v_lshlrev_b32_e32 v34, 7, v34
	v_add_u32_e32 v76, v231, v20
	v_add_u32_e32 v78, v231, v6
	v_add_u32_e32 v80, v231, v22
	v_add_u32_e32 v82, v231, v4
	v_add_u32_e32 v74, v231, v74
	v_add_u32_e32 v70, v231, v70
	v_add_u32_e32 v84, v231, v24
	v_add_u32_e32 v86, v231, v10
	v_add_u32_e32 v88, v231, v26
	v_add_u32_e32 v90, v231, v8
	v_add_u32_e32 v92, v231, v32
	v_add_u32_e32 v94, v231, v18
	v_add_u32_e32 v96, v231, v34
	v_add_u32_e32 v98, v231, v16
	global_load_dwordx4 v[4:7], v76, s[100:101]
	global_load_dwordx4 v[8:11], v78, s[100:101]
	global_load_dwordx4 v[16:19], v80, s[100:101]
	global_load_dwordx4 v[20:23], v82, s[100:101]
	global_load_dwordx4 v[24:27], v84, s[100:101]
	global_load_dwordx4 v[32:35], v86, s[100:101]
	global_load_dwordx4 v[36:39], v88, s[100:101]
	global_load_dwordx4 v[40:43], v90, s[100:101]
	global_load_dwordx4 v[44:47], v92, s[100:101]
	global_load_dwordx4 v[48:51], v94, s[100:101]
	global_load_dwordx4 v[56:59], v96, s[100:101]
	global_load_dwordx4 v[64:67], v98, s[100:101]
	global_load_dwordx4 v[76:79], v74, s[100:101]
	global_load_dwordx4 v[80:83], v70, s[100:101]
	v_mov_b32_e32 v70, v69
	v_lshlrev_b32_e32 v68, 7, v68
	v_lshlrev_b32_e32 v70, 7, v70
	v_add_u32_e32 v70, v231, v70
	v_add_u32_e32 v68, v231, v68
	global_load_dwordx4 v[84:87], v70, s[100:101]
	global_load_dwordx4 v[88:91], v68, s[100:101]
	v_add_u32_e32 v68, v63, v194
	v_ashrrev_i32_e32 v69, 31, v68
	v_lshlrev_b64 v[68:69], 9, v[68:69]
	v_lshl_add_u64 v[68:69], s[86:87], 0, v[68:69]
	v_lshl_add_u64 v[68:69], v[68:69], 0, v[72:73]
	v_lshl_add_u64 v[234:235], v[68:69], 0, v[232:233]
	global_load_dwordx2 v[240:241], v[234:235], off
	v_and_b32_e32 v68, 32, v62
	v_cmp_eq_u32_e32 vcc, 0, v68
	v_mbcnt_lo_u32_b32 v68, -1, 0
	v_mbcnt_hi_u32_b32 v68, -1, v68
	v_and_b32_e32 v70, 64, v68
	v_xor_b32_e32 v69, 32, v68
	v_add_u32_e32 v70, 64, v70
	v_cmp_lt_i32_e64 s[2:3], v69, v70
	v_and_b32_e32 v63, 63, v62
	s_nop 0
	v_cndmask_b32_e64 v69, v68, v69, s[2:3]
	v_lshlrev_b32_e32 v210, 2, v69
	v_and_b32_e32 v69, 16, v62
	v_cmp_eq_u32_e64 s[2:3], 0, v69
	v_xor_b32_e32 v69, 16, v68
	v_cmp_lt_i32_e64 s[4:5], v69, v70
	s_nop 1
	v_cndmask_b32_e64 v69, v68, v69, s[4:5]
	v_lshlrev_b32_e32 v211, 2, v69
	v_and_b32_e32 v69, 8, v62
	v_cmp_eq_u32_e64 s[4:5], 0, v69
	v_xor_b32_e32 v69, 8, v68
	v_cmp_lt_i32_e64 s[6:7], v69, v70
	s_nop 1
	v_cndmask_b32_e64 v69, v68, v69, s[6:7]
	v_lshlrev_b32_e32 v212, 2, v69
	v_xor_b32_e32 v69, 4, v68
	v_cmp_lt_i32_e64 s[6:7], v69, v70
	s_nop 1
	v_cndmask_b32_e64 v69, v68, v69, s[6:7]
	v_lshlrev_b32_e32 v213, 2, v69
	v_xor_b32_e32 v69, 2, v68
	v_cmp_lt_i32_e64 s[6:7], v69, v70
	s_nop 1
	v_cndmask_b32_e64 v69, v68, v69, s[6:7]
	v_lshlrev_b32_e32 v214, 2, v69
	v_xor_b32_e32 v69, 1, v68
	v_cmp_lt_i32_e64 s[6:7], v69, v70
	s_nop 1
	v_cndmask_b32_e64 v68, v68, v69, s[6:7]
	v_lshlrev_b32_e32 v215, 2, v68
	v_lshl_add_u64 v[68:69], s[8:9], 0, v[60:61]
	v_and_b32_e32 v60, 56, v62
	v_cmp_eq_u32_e64 s[6:7], 0, v63
	v_lshl_add_u64 v[202:203], v[68:69], 0, v[60:61]
	s_branch .LBB0_1477

; DI void peer_v_phase(const Params& p) {
;     ...
;   auto gather = [&](PeerVRows& r, const int* e, int tok) {
; #pragma unroll
;     for (int i = 0; i < 16; ++i) r.v[i] = *(const u32x4*)(Vb + (size_t)e[i] * 128);
;     const float4* wp = (const float4*)(W + (size_t)tok * 128 + 16 * q);
; #pragma unroll
;     for (int j = 0; j < 4; ++j) r.w[j] = wp[j];
;   };
;     ...
;   for (int k = 0; k < n; k += 2) {
;     peer_load_e(ea, EID, tokof(k + 2), q);
;     gather(gb, eb, tokof(k + 1));
.LBB0_1477:
	s_add_i32 s19, s1, -1
	v_min_i32_e32 v60, s19, v195
	s_waitcnt lgkmcnt(0)
	v_mad_u64_u32 v[60:61], s[8:9], v60, s18, v[194:195]
	v_ashrrev_i32_e32 v61, 31, v60
	v_lshlrev_b64 v[208:209], 9, v[60:61]
	v_lshl_add_u64 v[60:61], v[198:199], 0, v[208:209]
	s_add_i32 s16, s1, -2
	v_lshl_add_u64 v[234:235], v[60:61], 0, v[232:233]
	global_load_dwordx2 v[236:237], v[234:235], off
	v_min_i32_e32 v60, s16, v195
	v_mad_u64_u32 v[206:207], s[8:9], v60, s18, v[194:195]
	s_waitcnt vmcnt(1)
	v_mov_b32_e32 v244, v242
	v_mov_b32_e32 v245, v243
	v_mov_b32_dpp v244, v242 row_shl:4 row_mask:0xf bank_mask:0x5
	v_mov_b32_dpp v245, v243 row_shl:4 row_mask:0xf bank_mask:0x5
	v_mov_b32_dpp v242, v242 row_shr:4 row_mask:0xf bank_mask:0xa
	v_mov_b32_dpp v243, v243 row_shr:4 row_mask:0xf bank_mask:0xa
	v_mov_b32_dpp v12, v244 quad_perm:[0,0,0,0] row_mask:0xf bank_mask:0xf
	v_mov_b32_dpp v13, v245 quad_perm:[0,0,0,0] row_mask:0xf bank_mask:0xf
	v_mov_b32_dpp v14, v244 quad_perm:[1,1,1,1] row_mask:0xf bank_mask:0xf
	v_mov_b32_dpp v15, v245 quad_perm:[1,1,1,1] row_mask:0xf bank_mask:0xf
	v_mov_b32_dpp v0, v244 quad_perm:[2,2,2,2] row_mask:0xf bank_mask:0xf
	v_mov_b32_dpp v1, v245 quad_perm:[2,2,2,2] row_mask:0xf bank_mask:0xf
	v_mov_b32_dpp v2, v244 quad_perm:[3,3,3,3] row_mask:0xf bank_mask:0xf
	v_mov_b32_dpp v3, v245 quad_perm:[3,3,3,3] row_mask:0xf bank_mask:0xf
	v_mov_b32_dpp v52, v242 quad_perm:[0,0,0,0] row_mask:0xf bank_mask:0xf
	v_mov_b32_dpp v53, v243 quad_perm:[0,0,0,0] row_mask:0xf bank_mask:0xf
	v_mov_b32_dpp v54, v242 quad_perm:[1,1,1,1] row_mask:0xf bank_mask:0xf
	v_mov_b32_dpp v55, v243 quad_perm:[1,1,1,1] row_mask:0xf bank_mask:0xf
	v_mov_b32_dpp v28, v242 quad_perm:[2,2,2,2] row_mask:0xf bank_mask:0xf
	v_mov_b32_dpp v29, v243 quad_perm:[2,2,2,2] row_mask:0xf bank_mask:0xf
	v_mov_b32_dpp v30, v242 quad_perm:[3,3,3,3] row_mask:0xf bank_mask:0xf
	v_mov_b32_dpp v31, v243 quad_perm:[3,3,3,3] row_mask:0xf bank_mask:0xf
	v_mov_b32_e32 v244, v240
	v_mov_b32_e32 v245, v241
	v_mov_b32_dpp v244, v240 row_shl:4 row_mask:0xf bank_mask:0x5
	v_mov_b32_dpp v245, v241 row_shl:4 row_mask:0xf bank_mask:0x5
	v_mov_b32_dpp v240, v240 row_shr:4 row_mask:0xf bank_mask:0xa
	v_mov_b32_dpp v241, v241 row_shr:4 row_mask:0xf bank_mask:0xa
	v_mov_b32_dpp v108, v244 quad_perm:[0,0,0,0] row_mask:0xf bank_mask:0xf
	v_mov_b32_dpp v109, v245 quad_perm:[0,0,0,0] row_mask:0xf bank_mask:0xf
	v_mov_b32_dpp v110, v244 quad_perm:[1,1,1,1] row_mask:0xf bank_mask:0xf
	v_mov_b32_dpp v111, v245 quad_perm:[1,1,1,1] row_mask:0xf bank_mask:0xf
	v_mov_b32_dpp v96, v244 quad_perm:[2,2,2,2] row_mask:0xf bank_mask:0xf
	v_mov_b32_dpp v97, v245 quad_perm:[2,2,2,2] row_mask:0xf bank_mask:0xf
	v_mov_b32_dpp v98, v244 quad_perm:[3,3,3,3] row_mask:0xf bank_mask:0xf
	v_mov_b32_dpp v99, v245 quad_perm:[3,3,3,3] row_mask:0xf bank_mask:0xf
	v_mov_b32_dpp v132, v240 quad_perm:[0,0,0,0] row_mask:0xf bank_mask:0xf
	v_mov_b32_dpp v133, v241 quad_perm:[0,0,0,0] row_mask:0xf bank_mask:0xf
	v_mov_b32_dpp v134, v240 quad_perm:[1,1,1,1] row_mask:0xf bank_mask:0xf
	v_mov_b32_dpp v135, v241 quad_perm:[1,1,1,1] row_mask:0xf bank_mask:0xf
	v_mov_b32_dpp v116, v240 quad_perm:[2,2,2,2] row_mask:0xf bank_mask:0xf
	v_mov_b32_dpp v117, v241 quad_perm:[2,2,2,2] row_mask:0xf bank_mask:0xf
	v_mov_b32_dpp v118, v240 quad_perm:[3,3,3,3] row_mask:0xf bank_mask:0xf
	v_mov_b32_dpp v119, v241 quad_perm:[3,3,3,3] row_mask:0xf bank_mask:0xf
	v_mov_b32_e32 v60, v132
	v_mov_b32_e32 v62, v133
	v_lshlrev_b32_e32 v60, 7, v60
	v_lshlrev_b32_e32 v62, 7, v62
	v_add_u32_e32 v60, v231, v60
	v_add_u32_e32 v62, v231, v62
	global_load_dwordx4 v[168:171], v60, s[100:101]
	global_load_dwordx4 v[164:167], v62, s[100:101]
	v_mov_b32_e32 v60, v134
	v_mov_b32_e32 v62, v135
	v_lshlrev_b32_e32 v60, 7, v60
	v_lshlrev_b32_e32 v62, 7, v62
	v_add_u32_e32 v60, v231, v60
	v_add_u32_e32 v62, v231, v62
	global_load_dwordx4 v[160:163], v60, s[100:101]
	global_load_dwordx4 v[152:155], v62, s[100:101]
	v_mov_b32_e32 v60, v116
	v_mov_b32_e32 v62, v117
	v_lshlrev_b32_e32 v60, 7, v60
	v_lshlrev_b32_e32 v62, 7, v62
	v_add_u32_e32 v60, v231, v60
	v_add_u32_e32 v62, v231, v62
	global_load_dwordx4 v[148:151], v60, s[100:101]
	global_load_dwordx4 v[144:147], v62, s[100:101]
	v_mov_b32_e32 v60, v118
	v_mov_b32_e32 v62, v119
	v_lshlrev_b32_e32 v60, 7, v60
	v_lshlrev_b32_e32 v62, 7, v62
	v_add_u32_e32 v60, v231, v60
	v_add_u32_e32 v62, v231, v62
	global_load_dwordx4 v[140:143], v60, s[100:101]
	global_load_dwordx4 v[136:139], v62, s[100:101]
	v_mov_b32_e32 v60, v108
	v_mov_b32_e32 v62, v109
	v_lshlrev_b32_e32 v60, 7, v60
	v_lshlrev_b32_e32 v62, 7, v62
	v_add_u32_e32 v60, v231, v60
	v_add_u32_e32 v62, v231, v62
	global_load_dwordx4 v[128:131], v60, s[100:101]
	global_load_dwordx4 v[120:123], v62, s[100:101]
	v_mov_b32_e32 v60, v110
	v_mov_b32_e32 v62, v111
	v_lshlrev_b32_e32 v60, 7, v60
	v_lshlrev_b32_e32 v62, 7, v62
	v_add_u32_e32 v60, v231, v60
	v_add_u32_e32 v62, v231, v62
	global_load_dwordx4 v[112:115], v60, s[100:101]
	global_load_dwordx4 v[104:107], v62, s[100:101]
	v_mov_b32_e32 v60, v96
	v_mov_b32_e32 v62, v97
	v_lshlrev_b32_e32 v60, 7, v60
	v_lshlrev_b32_e32 v62, 7, v62
	v_add_u32_e32 v60, v231, v60
	v_add_u32_e32 v62, v231, v62
	global_load_dwordx4 v[100:103], v60, s[100:101]
	global_load_dwordx4 v[92:95], v62, s[100:101]
	v_mov_b32_e32 v60, v98
	v_mov_b32_e32 v62, v99
	v_ashrrev_i32_e32 v207, 31, v206
	v_lshlrev_b32_e32 v60, 7, v60
	v_lshlrev_b32_e32 v62, 7, v62
	v_lshlrev_b64 v[72:73], 9, v[206:207]
	v_add_u32_e32 v60, v231, v60
	v_add_u32_e32 v62, v231, v62
	v_lshl_add_u64 v[96:97], v[200:201], 0, v[72:73]
	global_load_dwordx4 v[68:71], v60, s[100:101]
; DI void peer_v_phase(const Params& p) {
;     ...
;   auto gather = [&](PeerVRows& r, const int* e, int tok) {
; #pragma unroll
;     for (int i = 0; i < 16; ++i) r.v[i] = *(const u32x4*)(Vb + (size_t)e[i] * 128);
;     const float4* wp = (const float4*)(W + (size_t)tok * 128 + 16 * q);
; #pragma unroll
;     for (int j = 0; j < 4; ++j) r.w[j] = wp[j];
;   };
;   auto compute = [&](const PeerVRows& r, int tok) {
;     f32x2 o2[8];
; #pragma unroll
;     for (int k = 0; k < 8; ++k) { o2[k][0] = 0.f; o2[k][1] = 0.f; }
; #pragma unroll
;     for (int i = 0; i < 16; ++i) {
;       const float wi = (i & 3) == 0 ? r.w[i >> 2].x : (i & 3) == 1 ? r.w[i >> 2].y : (i & 3) == 2 ? r.w[i >> 2].z : r.w[i >> 2].w;
;       const f32x2 w2 = {wi, wi};
; #pragma unroll
;       for (int j = 0; j < 4; ++j) {
;         const f32x2 lo = __builtin_amdgcn_cvt_pk_f32_fp8((int)r.v[i][j], false);
;         const f32x2 hi = __builtin_amdgcn_cvt_pk_f32_fp8((int)r.v[i][j], true);
;         o2[2 * j] = __builtin_elementwise_fma(lo, w2, o2[2 * j]);
;         o2[2 * j + 1] = __builtin_elementwise_fma(hi, w2, o2[2 * j + 1]);
;       }
;     }
;     float o[16];
	s_nop 0
	global_load_dwordx4 v[60:63], v62, s[100:101]
	s_nop 0
	v_lshl_add_u64 v[234:235], v[96:97], 0, v[232:233]
	global_load_dwordx2 v[238:239], v[234:235], off
	v_cvt_pk_f32_fp8_e32 v[96:97], v88
	v_cvt_pk_f32_fp8_sdwa v[98:99], v88 src0_sel:WORD_1
	v_cvt_pk_f32_fp8_e32 v[108:109], v89
	v_cvt_pk_f32_fp8_sdwa v[88:89], v89 src0_sel:WORD_1
	v_cvt_pk_f32_fp8_e32 v[132:133], v84
	v_cvt_pk_f32_fp8_sdwa v[134:135], v84 src0_sel:WORD_1
	v_cvt_pk_f32_fp8_e32 v[216:217], v85
	v_cvt_pk_f32_fp8_sdwa v[84:85], v85 src0_sel:WORD_1
	v_pk_fma_f32 v[96:97], v[96:97], v[52:53], 0 op_sel_hi:[1,0,0]
	v_pk_fma_f32 v[98:99], v[98:99], v[52:53], 0 op_sel_hi:[1,0,0]
	v_pk_fma_f32 v[88:89], v[88:89], v[52:53], 0 op_sel_hi:[1,0,0]
	v_cvt_pk_f32_fp8_e32 v[110:111], v90
	v_cvt_pk_f32_fp8_sdwa v[116:117], v90 src0_sel:WORD_1
	v_cvt_pk_f32_fp8_e32 v[118:119], v91
	v_cvt_pk_f32_fp8_sdwa v[90:91], v91 src0_sel:WORD_1
	v_pk_fma_f32 v[96:97], v[132:133], v[52:53], v[96:97] op_sel:[0,1,0]
	v_pk_fma_f32 v[98:99], v[134:135], v[52:53], v[98:99] op_sel:[0,1,0]
	v_pk_fma_f32 v[84:85], v[84:85], v[52:53], v[88:89] op_sel:[0,1,0]
	v_cvt_pk_f32_fp8_e32 v[88:89], v86
	v_cvt_pk_f32_fp8_sdwa v[132:133], v86 src0_sel:WORD_1
	v_cvt_pk_f32_fp8_e32 v[134:135], v87
	v_cvt_pk_f32_fp8_sdwa v[86:87], v87 src0_sel:WORD_1
	v_pk_fma_f32 v[108:109], v[108:109], v[52:53], 0 op_sel_hi:[1,0,0]
	v_pk_fma_f32 v[110:111], v[110:111], v[52:53], 0 op_sel_hi:[1,0,0]
	v_pk_fma_f32 v[116:117], v[116:117], v[52:53], 0 op_sel_hi:[1,0,0]
	v_pk_fma_f32 v[118:119], v[118:119], v[52:53], 0 op_sel_hi:[1,0,0]
	v_pk_fma_f32 v[90:91], v[90:91], v[52:53], 0 op_sel_hi:[1,0,0]
	v_pk_fma_f32 v[108:109], v[216:217], v[52:53], v[108:109] op_sel:[0,1,0]
	v_pk_fma_f32 v[88:89], v[88:89], v[52:53], v[110:111] op_sel:[0,1,0]
	v_pk_fma_f32 v[110:111], v[132:133], v[52:53], v[116:117] op_sel:[0,1,0]
	v_pk_fma_f32 v[116:117], v[134:135], v[52:53], v[118:119] op_sel:[0,1,0]
	v_pk_fma_f32 v[52:53], v[86:87], v[52:53], v[90:91] op_sel:[0,1,0]
	v_cvt_pk_f32_fp8_e32 v[86:87], v80
	v_cvt_pk_f32_fp8_sdwa v[90:91], v80 src0_sel:WORD_1
	v_cvt_pk_f32_fp8_e32 v[118:119], v81
	v_cvt_pk_f32_fp8_sdwa v[80:81], v81 src0_sel:WORD_1
	v_pk_fma_f32 v[86:87], v[86:87], v[54:55], v[96:97] op_sel_hi:[1,0,1]
	v_pk_fma_f32 v[90:91], v[90:91], v[54:55], v[98:99] op_sel_hi:[1,0,1]
	v_pk_fma_f32 v[96:97], v[118:119], v[54:55], v[108:109] op_sel_hi:[1,0,1]
	v_pk_fma_f32 v[80:81], v[80:81], v[54:55], v[84:85] op_sel_hi:[1,0,1]
	v_cvt_pk_f32_fp8_e32 v[84:85], v82
	v_cvt_pk_f32_fp8_sdwa v[98:99], v82 src0_sel:WORD_1
	v_cvt_pk_f32_fp8_e32 v[108:109], v83
	v_cvt_pk_f32_fp8_sdwa v[82:83], v83 src0_sel:WORD_1
	v_pk_fma_f32 v[84:85], v[84:85], v[54:55], v[88:89] op_sel_hi:[1,0,1]
	v_pk_fma_f32 v[88:89], v[98:99], v[54:55], v[110:111] op_sel_hi:[1,0,1]
	v_pk_fma_f32 v[98:99], v[108:109], v[54:55], v[116:117] op_sel_hi:[1,0,1]
	v_pk_fma_f32 v[52:53], v[82:83], v[54:55], v[52:53] op_sel_hi:[1,0,1]
	v_cvt_pk_f32_fp8_e32 v[82:83], v76
	v_cvt_pk_f32_fp8_sdwa v[108:109], v76 src0_sel:WORD_1
	v_cvt_pk_f32_fp8_e32 v[110:111], v77
	v_cvt_pk_f32_fp8_sdwa v[76:77], v77 src0_sel:WORD_1
	v_pk_fma_f32 v[82:83], v[82:83], v[54:55], v[86:87] op_sel:[0,1,0]
	v_pk_fma_f32 v[86:87], v[108:109], v[54:55], v[90:91] op_sel:[0,1,0]
	v_pk_fma_f32 v[90:91], v[110:111], v[54:55], v[96:97] op_sel:[0,1,0]
	v_pk_fma_f32 v[76:77], v[76:77], v[54:55], v[80:81] op_sel:[0,1,0]
	v_cvt_pk_f32_fp8_e32 v[80:81], v78
	v_cvt_pk_f32_fp8_sdwa v[96:97], v78 src0_sel:WORD_1
	v_cvt_pk_f32_fp8_e32 v[108:109], v79
	v_cvt_pk_f32_fp8_sdwa v[78:79], v79 src0_sel:WORD_1
	v_pk_fma_f32 v[80:81], v[80:81], v[54:55], v[84:85] op_sel:[0,1,0]
	v_pk_fma_f32 v[84:85], v[96:97], v[54:55], v[88:89] op_sel:[0,1,0]
	v_pk_fma_f32 v[88:89], v[108:109], v[54:55], v[98:99] op_sel:[0,1,0]
	v_pk_fma_f32 v[52:53], v[78:79], v[54:55], v[52:53] op_sel:[0,1,0]
	v_cvt_pk_f32_fp8_e32 v[54:55], v64
	v_cvt_pk_f32_fp8_sdwa v[78:79], v64 src0_sel:WORD_1
	v_cvt_pk_f32_fp8_e32 v[96:97], v65
	v_cvt_pk_f32_fp8_sdwa v[64:65], v65 src0_sel:WORD_1
	v_pk_fma_f32 v[54:55], v[54:55], v[28:29], v[82:83] op_sel_hi:[1,0,1]
	v_pk_fma_f32 v[78:79], v[78:79], v[28:29], v[86:87] op_sel_hi:[1,0,1]
	v_pk_fma_f32 v[82:83], v[96:97], v[28:29], v[90:91] op_sel_hi:[1,0,1]
	v_pk_fma_f32 v[64:65], v[64:65], v[28:29], v[76:77] op_sel_hi:[1,0,1]
	v_cvt_pk_f32_fp8_e32 v[76:77], v66
	v_cvt_pk_f32_fp8_sdwa v[86:87], v66 src0_sel:WORD_1
	v_cvt_pk_f32_fp8_e32 v[90:91], v67
	v_cvt_pk_f32_fp8_sdwa v[66:67], v67 src0_sel:WORD_1
	v_pk_fma_f32 v[76:77], v[76:77], v[28:29], v[80:81] op_sel_hi:[1,0,1]
	v_pk_fma_f32 v[80:81], v[86:87], v[28:29], v[84:85] op_sel_hi:[1,0,1]
	v_pk_fma_f32 v[84:85], v[90:91], v[28:29], v[88:89] op_sel_hi:[1,0,1]
	v_pk_fma_f32 v[52:53], v[66:67], v[28:29], v[52:53] op_sel_hi:[1,0,1]
	v_cvt_pk_f32_fp8_e32 v[66:67], v56
	v_cvt_pk_f32_fp8_sdwa v[86:87], v56 src0_sel:WORD_1
	v_cvt_pk_f32_fp8_e32 v[88:89], v57
	v_cvt_pk_f32_fp8_sdwa v[56:57], v57 src0_sel:WORD_1
	v_pk_fma_f32 v[54:55], v[66:67], v[28:29], v[54:55] op_sel:[0,1,0]
	v_pk_fma_f32 v[66:67], v[86:87], v[28:29], v[78:79] op_sel:[0,1,0]
	v_pk_fma_f32 v[78:79], v[88:89], v[28:29], v[82:83] op_sel:[0,1,0]
	v_pk_fma_f32 v[56:57], v[56:57], v[28:29], v[64:65] op_sel:[0,1,0]
	v_cvt_pk_f32_fp8_e32 v[64:65], v58
	v_cvt_pk_f32_fp8_sdwa v[82:83], v58 src0_sel:WORD_1
	v_cvt_pk_f32_fp8_e32 v[86:87], v59
	v_cvt_pk_f32_fp8_sdwa v[58:59], v59 src0_sel:WORD_1
	v_pk_fma_f32 v[64:65], v[64:65], v[28:29], v[76:77] op_sel:[0,1,0]
	v_pk_fma_f32 v[76:77], v[82:83], v[28:29], v[80:81] op_sel:[0,1,0]
	v_pk_fma_f32 v[80:81], v[86:87], v[28:29], v[84:85] op_sel:[0,1,0]
	v_pk_fma_f32 v[28:29], v[58:59], v[28:29], v[52:53] op_sel:[0,1,0]
; DI void peer_v_phase(const Params& p) {
;     ...
; #pragma unroll
;     for (int i = 0; i < 16; ++i) {
;       const float wi = (i & 3) == 0 ? r.w[i >> 2].x : (i & 3) == 1 ? r.w[i >> 2].y : (i & 3) == 2 ? r.w[i >> 2].z : r.w[i >> 2].w;
;       const f32x2 w2 = {wi, wi};
; #pragma unroll
;       for (int j = 0; j < 4; ++j) {
;         const f32x2 lo = __builtin_amdgcn_cvt_pk_f32_fp8((int)r.v[i][j], false);
;         const f32x2 hi = __builtin_amdgcn_cvt_pk_f32_fp8((int)r.v[i][j], true);
;         o2[2 * j] = __builtin_elementwise_fma(lo, w2, o2[2 * j]);
;         o2[2 * j + 1] = __builtin_elementwise_fma(hi, w2, o2[2 * j + 1]);
;       }
;     }
	v_cvt_pk_f32_fp8_e32 v[52:53], v48
	v_cvt_pk_f32_fp8_sdwa v[58:59], v48 src0_sel:WORD_1
	v_cvt_pk_f32_fp8_e32 v[82:83], v49
	v_cvt_pk_f32_fp8_sdwa v[48:49], v49 src0_sel:WORD_1
	v_pk_fma_f32 v[52:53], v[52:53], v[30:31], v[54:55] op_sel_hi:[1,0,1]
	v_pk_fma_f32 v[54:55], v[58:59], v[30:31], v[66:67] op_sel_hi:[1,0,1]
	v_pk_fma_f32 v[58:59], v[82:83], v[30:31], v[78:79] op_sel_hi:[1,0,1]
	v_pk_fma_f32 v[48:49], v[48:49], v[30:31], v[56:57] op_sel_hi:[1,0,1]
	v_cvt_pk_f32_fp8_e32 v[56:57], v50
	v_cvt_pk_f32_fp8_sdwa v[66:67], v50 src0_sel:WORD_1
	v_cvt_pk_f32_fp8_e32 v[78:79], v51
	v_cvt_pk_f32_fp8_sdwa v[50:51], v51 src0_sel:WORD_1
	v_pk_fma_f32 v[56:57], v[56:57], v[30:31], v[64:65] op_sel_hi:[1,0,1]
	v_pk_fma_f32 v[64:65], v[66:67], v[30:31], v[76:77] op_sel_hi:[1,0,1]
	v_pk_fma_f32 v[66:67], v[78:79], v[30:31], v[80:81] op_sel_hi:[1,0,1]
	v_pk_fma_f32 v[28:29], v[50:51], v[30:31], v[28:29] op_sel_hi:[1,0,1]
	v_cvt_pk_f32_fp8_e32 v[50:51], v44
	v_cvt_pk_f32_fp8_sdwa v[76:77], v44 src0_sel:WORD_1
	v_cvt_pk_f32_fp8_e32 v[78:79], v45
	v_cvt_pk_f32_fp8_sdwa v[44:45], v45 src0_sel:WORD_1
	v_pk_fma_f32 v[50:51], v[50:51], v[30:31], v[52:53] op_sel:[0,1,0]
	v_pk_fma_f32 v[52:53], v[76:77], v[30:31], v[54:55] op_sel:[0,1,0]
	v_pk_fma_f32 v[54:55], v[78:79], v[30:31], v[58:59] op_sel:[0,1,0]
	v_pk_fma_f32 v[44:45], v[44:45], v[30:31], v[48:49] op_sel:[0,1,0]
	v_cvt_pk_f32_fp8_e32 v[48:49], v46
	v_cvt_pk_f32_fp8_sdwa v[58:59], v46 src0_sel:WORD_1
	v_cvt_pk_f32_fp8_e32 v[76:77], v47
	v_cvt_pk_f32_fp8_sdwa v[46:47], v47 src0_sel:WORD_1
	v_pk_fma_f32 v[48:49], v[48:49], v[30:31], v[56:57] op_sel:[0,1,0]
	v_pk_fma_f32 v[56:57], v[58:59], v[30:31], v[64:65] op_sel:[0,1,0]
	v_pk_fma_f32 v[58:59], v[76:77], v[30:31], v[66:67] op_sel:[0,1,0]
	v_pk_fma_f32 v[28:29], v[46:47], v[30:31], v[28:29] op_sel:[0,1,0]
	v_cvt_pk_f32_fp8_e32 v[30:31], v40
	v_cvt_pk_f32_fp8_sdwa v[46:47], v40 src0_sel:WORD_1
	v_cvt_pk_f32_fp8_e32 v[64:65], v41
	v_cvt_pk_f32_fp8_sdwa v[40:41], v41 src0_sel:WORD_1
	v_pk_fma_f32 v[30:31], v[30:31], v[12:13], v[50:51] op_sel_hi:[1,0,1]
	v_pk_fma_f32 v[46:47], v[46:47], v[12:13], v[52:53] op_sel_hi:[1,0,1]
	v_pk_fma_f32 v[50:51], v[64:65], v[12:13], v[54:55] op_sel_hi:[1,0,1]
	v_pk_fma_f32 v[40:41], v[40:41], v[12:13], v[44:45] op_sel_hi:[1,0,1]
	v_cvt_pk_f32_fp8_e32 v[44:45], v42
	v_cvt_pk_f32_fp8_sdwa v[52:53], v42 src0_sel:WORD_1
	v_cvt_pk_f32_fp8_e32 v[54:55], v43
	v_cvt_pk_f32_fp8_sdwa v[42:43], v43 src0_sel:WORD_1
	v_pk_fma_f32 v[44:45], v[44:45], v[12:13], v[48:49] op_sel_hi:[1,0,1]
	v_pk_fma_f32 v[48:49], v[52:53], v[12:13], v[56:57] op_sel_hi:[1,0,1]
	v_pk_fma_f32 v[52:53], v[54:55], v[12:13], v[58:59] op_sel_hi:[1,0,1]
	v_pk_fma_f32 v[28:29], v[42:43], v[12:13], v[28:29] op_sel_hi:[1,0,1]
	v_cvt_pk_f32_fp8_e32 v[42:43], v36
	v_cvt_pk_f32_fp8_sdwa v[54:55], v36 src0_sel:WORD_1
	v_cvt_pk_f32_fp8_e32 v[56:57], v37
	v_cvt_pk_f32_fp8_sdwa v[36:37], v37 src0_sel:WORD_1
	v_pk_fma_f32 v[30:31], v[42:43], v[12:13], v[30:31] op_sel:[0,1,0]
	v_pk_fma_f32 v[42:43], v[54:55], v[12:13], v[46:47] op_sel:[0,1,0]
	v_pk_fma_f32 v[46:47], v[56:57], v[12:13], v[50:51] op_sel:[0,1,0]
	v_pk_fma_f32 v[36:37], v[36:37], v[12:13], v[40:41] op_sel:[0,1,0]
	v_cvt_pk_f32_fp8_e32 v[40:41], v38
	v_cvt_pk_f32_fp8_sdwa v[50:51], v38 src0_sel:WORD_1
	v_cvt_pk_f32_fp8_e32 v[54:55], v39
	v_cvt_pk_f32_fp8_sdwa v[38:39], v39 src0_sel:WORD_1
	v_pk_fma_f32 v[40:41], v[40:41], v[12:13], v[44:45] op_sel:[0,1,0]
	v_pk_fma_f32 v[44:45], v[50:51], v[12:13], v[48:49] op_sel:[0,1,0]
	v_pk_fma_f32 v[48:49], v[54:55], v[12:13], v[52:53] op_sel:[0,1,0]
	v_pk_fma_f32 v[12:13], v[38:39], v[12:13], v[28:29] op_sel:[0,1,0]
	v_cvt_pk_f32_fp8_e32 v[28:29], v32
	v_cvt_pk_f32_fp8_sdwa v[38:39], v32 src0_sel:WORD_1
	v_cvt_pk_f32_fp8_e32 v[50:51], v33
	v_cvt_pk_f32_fp8_sdwa v[32:33], v33 src0_sel:WORD_1
	v_pk_fma_f32 v[28:29], v[28:29], v[14:15], v[30:31] op_sel_hi:[1,0,1]
	v_pk_fma_f32 v[30:31], v[38:39], v[14:15], v[42:43] op_sel_hi:[1,0,1]
	v_pk_fma_f32 v[38:39], v[50:51], v[14:15], v[46:47] op_sel_hi:[1,0,1]
	v_pk_fma_f32 v[32:33], v[32:33], v[14:15], v[36:37] op_sel_hi:[1,0,1]
	v_cvt_pk_f32_fp8_e32 v[36:37], v34
	v_cvt_pk_f32_fp8_sdwa v[42:43], v34 src0_sel:WORD_1
	v_cvt_pk_f32_fp8_e32 v[46:47], v35
	v_cvt_pk_f32_fp8_sdwa v[34:35], v35 src0_sel:WORD_1
	v_pk_fma_f32 v[36:37], v[36:37], v[14:15], v[40:41] op_sel_hi:[1,0,1]
	v_pk_fma_f32 v[40:41], v[42:43], v[14:15], v[44:45] op_sel_hi:[1,0,1]
	v_pk_fma_f32 v[42:43], v[46:47], v[14:15], v[48:49] op_sel_hi:[1,0,1]
	v_pk_fma_f32 v[12:13], v[34:35], v[14:15], v[12:13] op_sel_hi:[1,0,1]
	v_cvt_pk_f32_fp8_e32 v[34:35], v24
	v_cvt_pk_f32_fp8_sdwa v[44:45], v24 src0_sel:WORD_1
	v_cvt_pk_f32_fp8_e32 v[46:47], v25
	v_cvt_pk_f32_fp8_sdwa v[24:25], v25 src0_sel:WORD_1
	v_pk_fma_f32 v[28:29], v[34:35], v[14:15], v[28:29] op_sel:[0,1,0]
	v_pk_fma_f32 v[30:31], v[44:45], v[14:15], v[30:31] op_sel:[0,1,0]
	v_pk_fma_f32 v[34:35], v[46:47], v[14:15], v[38:39] op_sel:[0,1,0]
	v_pk_fma_f32 v[24:25], v[24:25], v[14:15], v[32:33] op_sel:[0,1,0]
	v_cvt_pk_f32_fp8_e32 v[32:33], v26
	v_cvt_pk_f32_fp8_sdwa v[38:39], v26 src0_sel:WORD_1
	v_cvt_pk_f32_fp8_e32 v[44:45], v27
	v_cvt_pk_f32_fp8_sdwa v[26:27], v27 src0_sel:WORD_1
	v_pk_fma_f32 v[32:33], v[32:33], v[14:15], v[36:37] op_sel:[0,1,0]
	v_pk_fma_f32 v[36:37], v[38:39], v[14:15], v[40:41] op_sel:[0,1,0]
	v_pk_fma_f32 v[38:39], v[44:45], v[14:15], v[42:43] op_sel:[0,1,0]
	v_pk_fma_f32 v[12:13], v[26:27], v[14:15], v[12:13] op_sel:[0,1,0]
	v_cvt_pk_f32_fp8_e32 v[14:15], v20
	v_cvt_pk_f32_fp8_sdwa v[26:27], v20 src0_sel:WORD_1
	v_cvt_pk_f32_fp8_e32 v[40:41], v21
	v_cvt_pk_f32_fp8_sdwa v[20:21], v21 src0_sel:WORD_1
; DI void peer_v_phase(const Params& p) {
;     ...
;       for (int j = 0; j < 4; ++j) {
;         const f32x2 lo = __builtin_amdgcn_cvt_pk_f32_fp8((int)r.v[i][j], false);
;         const f32x2 hi = __builtin_amdgcn_cvt_pk_f32_fp8((int)r.v[i][j], true);
;         o2[2 * j] = __builtin_elementwise_fma(lo, w2, o2[2 * j]);
;         o2[2 * j + 1] = __builtin_elementwise_fma(hi, w2, o2[2 * j + 1]);
;       }
;     }
;     float o[16];
; #pragma unroll
;     for (int k = 0; k < 8; ++k) { o[2 * k] = o2[k][0]; o[2 * k + 1] = o2[k][1]; }
;     float r8[8], r4[4], r2[2];
; #pragma unroll
;     for (int k = 0; k < 8; ++k) {
;       const float keep = (lane & 32) ? o[k + 8] : o[k], send = (lane & 32) ? o[k] : o[k + 8];
;       r8[k] = keep + __shfl_xor(send, 32);
;     }
; #pragma unroll
;     for (int k = 0; k < 4; ++k) {
;       const float keep = (lane & 16) ? r8[k + 4] : r8[k], send = (lane & 16) ? r8[k] : r8[k + 4];
;       r4[k] = keep + __shfl_xor(send, 16);
;     }
; #pragma unroll
;     for (int k = 0; k < 2; ++k) {
;       const float keep = (lane & 8) ? r4[k + 2] : r4[k], send = (lane & 8) ? r4[k] : r4[k + 2];
;       r2[k] = keep + __shfl_xor(send, 8);
;     }
;     float* xr = p.out + (size_t)tok * 1024 + 128 * g + 16 * s + 2 * q;
;     float2 y = *(const float2*)xr;
;     y.x += r2[0]; y.y += r2[1];
;     *(float2*)xr = y;
	v_pk_fma_f32 v[14:15], v[14:15], v[0:1], v[28:29] op_sel_hi:[1,0,1]
	v_pk_fma_f32 v[26:27], v[26:27], v[0:1], v[30:31] op_sel_hi:[1,0,1]
	v_pk_fma_f32 v[28:29], v[40:41], v[0:1], v[34:35] op_sel_hi:[1,0,1]
	v_pk_fma_f32 v[20:21], v[20:21], v[0:1], v[24:25] op_sel_hi:[1,0,1]
	v_cvt_pk_f32_fp8_e32 v[24:25], v22
	v_cvt_pk_f32_fp8_sdwa v[30:31], v22 src0_sel:WORD_1
	v_cvt_pk_f32_fp8_e32 v[34:35], v23
	v_cvt_pk_f32_fp8_sdwa v[22:23], v23 src0_sel:WORD_1
	v_pk_fma_f32 v[24:25], v[24:25], v[0:1], v[32:33] op_sel_hi:[1,0,1]
	v_pk_fma_f32 v[30:31], v[30:31], v[0:1], v[36:37] op_sel_hi:[1,0,1]
	v_pk_fma_f32 v[32:33], v[34:35], v[0:1], v[38:39] op_sel_hi:[1,0,1]
	v_pk_fma_f32 v[12:13], v[22:23], v[0:1], v[12:13] op_sel_hi:[1,0,1]
	v_cvt_pk_f32_fp8_e32 v[22:23], v16
	v_cvt_pk_f32_fp8_sdwa v[34:35], v16 src0_sel:WORD_1
	v_cvt_pk_f32_fp8_e32 v[36:37], v17
	v_cvt_pk_f32_fp8_sdwa v[16:17], v17 src0_sel:WORD_1
	v_pk_fma_f32 v[14:15], v[22:23], v[0:1], v[14:15] op_sel:[0,1,0]
	v_pk_fma_f32 v[22:23], v[34:35], v[0:1], v[26:27] op_sel:[0,1,0]
	v_pk_fma_f32 v[26:27], v[36:37], v[0:1], v[28:29] op_sel:[0,1,0]
	v_pk_fma_f32 v[16:17], v[16:17], v[0:1], v[20:21] op_sel:[0,1,0]
	v_cvt_pk_f32_fp8_e32 v[20:21], v18
	v_cvt_pk_f32_fp8_sdwa v[28:29], v18 src0_sel:WORD_1
	v_cvt_pk_f32_fp8_e32 v[34:35], v19
	v_ashrrev_i32_e32 v205, 31, v204
	v_pk_fma_f32 v[20:21], v[20:21], v[0:1], v[24:25] op_sel:[0,1,0]
	v_pk_fma_f32 v[24:25], v[28:29], v[0:1], v[30:31] op_sel:[0,1,0]
	v_pk_fma_f32 v[28:29], v[34:35], v[0:1], v[32:33] op_sel:[0,1,0]
	v_lshlrev_b64 v[32:33], 12, v[204:205]
	v_lshl_add_u64 v[32:33], v[202:203], 0, v[32:33]
	global_load_dwordx2 v[34:35], v[32:33], off
	v_cvt_pk_f32_fp8_sdwa v[18:19], v19 src0_sel:WORD_1
	v_cvt_pk_f32_fp8_e32 v[30:31], v9
	v_pk_fma_f32 v[0:1], v[18:19], v[0:1], v[12:13] op_sel:[0,1,0]
	v_cvt_pk_f32_fp8_e32 v[12:13], v8
	v_cvt_pk_f32_fp8_sdwa v[18:19], v8 src0_sel:WORD_1
	v_cvt_pk_f32_fp8_sdwa v[8:9], v9 src0_sel:WORD_1
	v_pk_fma_f32 v[12:13], v[12:13], v[2:3], v[14:15] op_sel_hi:[1,0,1]
	v_pk_fma_f32 v[14:15], v[18:19], v[2:3], v[22:23] op_sel_hi:[1,0,1]
	v_pk_fma_f32 v[18:19], v[30:31], v[2:3], v[26:27] op_sel_hi:[1,0,1]
	v_pk_fma_f32 v[8:9], v[8:9], v[2:3], v[16:17] op_sel_hi:[1,0,1]
	v_cvt_pk_f32_fp8_e32 v[16:17], v10
	v_cvt_pk_f32_fp8_sdwa v[22:23], v10 src0_sel:WORD_1
	v_cvt_pk_f32_fp8_e32 v[26:27], v11
	v_cvt_pk_f32_fp8_sdwa v[10:11], v11 src0_sel:WORD_1
	v_pk_fma_f32 v[16:17], v[16:17], v[2:3], v[20:21] op_sel_hi:[1,0,1]
	v_pk_fma_f32 v[20:21], v[22:23], v[2:3], v[24:25] op_sel_hi:[1,0,1]
	v_pk_fma_f32 v[22:23], v[26:27], v[2:3], v[28:29] op_sel_hi:[1,0,1]
	v_pk_fma_f32 v[0:1], v[10:11], v[2:3], v[0:1] op_sel_hi:[1,0,1]
	v_cvt_pk_f32_fp8_e32 v[10:11], v4
	v_cvt_pk_f32_fp8_sdwa v[24:25], v4 src0_sel:WORD_1
	v_cvt_pk_f32_fp8_e32 v[26:27], v5
	v_cvt_pk_f32_fp8_sdwa v[4:5], v5 src0_sel:WORD_1
	v_pk_fma_f32 v[10:11], v[10:11], v[2:3], v[12:13] op_sel:[0,1,0]
	v_pk_fma_f32 v[12:13], v[24:25], v[2:3], v[14:15] op_sel:[0,1,0]
	v_pk_fma_f32 v[14:15], v[26:27], v[2:3], v[18:19] op_sel:[0,1,0]
	v_pk_fma_f32 v[4:5], v[4:5], v[2:3], v[8:9] op_sel:[0,1,0]
	v_cvt_pk_f32_fp8_e32 v[8:9], v6
	v_cvt_pk_f32_fp8_sdwa v[18:19], v6 src0_sel:WORD_1
	v_cvt_pk_f32_fp8_e32 v[24:25], v7
	v_cvt_pk_f32_fp8_sdwa v[6:7], v7 src0_sel:WORD_1
	v_pk_fma_f32 v[8:9], v[8:9], v[2:3], v[16:17] op_sel:[0,1,0]
	v_pk_fma_f32 v[16:17], v[18:19], v[2:3], v[20:21] op_sel:[0,1,0]
	v_pk_fma_f32 v[18:19], v[24:25], v[2:3], v[22:23] op_sel:[0,1,0]
	v_pk_fma_f32 v[0:1], v[6:7], v[2:3], v[0:1] op_sel:[0,1,0]
	v_cndmask_b32_e32 v2, v10, v8, vcc
	v_cndmask_b32_e32 v3, v11, v9, vcc
	ds_bpermute_b32 v2, v210, v2
	ds_bpermute_b32 v3, v210, v3
	v_cndmask_b32_e32 v6, v12, v16, vcc
	v_cndmask_b32_e32 v7, v13, v17, vcc
	ds_bpermute_b32 v6, v210, v6
	ds_bpermute_b32 v7, v210, v7
	v_cndmask_b32_e32 v20, v14, v18, vcc
	v_cndmask_b32_e32 v21, v15, v19, vcc
	ds_bpermute_b32 v20, v210, v20
	ds_bpermute_b32 v21, v210, v21
	v_cndmask_b32_e32 v22, v4, v0, vcc
	v_cndmask_b32_e32 v23, v5, v1, vcc
	ds_bpermute_b32 v22, v210, v22
	ds_bpermute_b32 v23, v210, v23
	v_cndmask_b32_e32 v9, v9, v11, vcc
	v_cndmask_b32_e32 v8, v8, v10, vcc
	s_waitcnt lgkmcnt(6)
	v_pk_add_f32 v[2:3], v[8:9], v[2:3]
	v_cndmask_b32_e32 v9, v17, v13, vcc
	v_cndmask_b32_e32 v8, v16, v12, vcc
	s_waitcnt lgkmcnt(4)
	v_pk_add_f32 v[6:7], v[8:9], v[6:7]
	v_cndmask_b32_e32 v9, v19, v15, vcc
	v_cndmask_b32_e32 v8, v18, v14, vcc
	s_waitcnt lgkmcnt(2)
	v_pk_add_f32 v[8:9], v[8:9], v[20:21]
	v_cndmask_b32_e32 v1, v1, v5, vcc
	v_cndmask_b32_e32 v0, v0, v4, vcc
	s_waitcnt lgkmcnt(0)
	v_pk_add_f32 v[0:1], v[0:1], v[22:23]
	v_cndmask_b32_e64 v11, v9, v3, s[2:3]
	v_cndmask_b32_e64 v3, v3, v9, s[2:3]
	ds_bpermute_b32 v5, v211, v3
	v_cndmask_b32_e64 v3, v6, v0, s[2:3]
	v_cndmask_b32_e64 v4, v2, v8, s[2:3]
	ds_bpermute_b32 v12, v211, v3
	v_cndmask_b32_e64 v3, v7, v1, s[2:3]
	ds_bpermute_b32 v4, v211, v4
	ds_bpermute_b32 v13, v211, v3
	v_cndmask_b32_e64 v10, v8, v2, s[2:3]
	v_cndmask_b32_e64 v1, v1, v7, s[2:3]
	v_cndmask_b32_e64 v0, v0, v6, s[2:3]
	s_waitcnt lgkmcnt(1)
	v_pk_add_f32 v[2:3], v[10:11], v[4:5]
	s_waitcnt lgkmcnt(0)
	v_pk_add_f32 v[0:1], v[0:1], v[12:13]
	s_nop 0
	v_cndmask_b32_e64 v4, v2, v0, s[4:5]
	v_cndmask_b32_e64 v5, v3, v1, s[4:5]
	ds_bpermute_b32 v4, v212, v4
	ds_bpermute_b32 v5, v212, v5
	v_cndmask_b32_e64 v1, v1, v3, s[4:5]
	v_cndmask_b32_e64 v0, v0, v2, s[4:5]
	s_waitcnt lgkmcnt(0)
	v_pk_add_f32 v[0:1], v[0:1], v[4:5]
	s_waitcnt vmcnt(0)
; DI void peer_v_phase(const Params& p) {
;     ...
;   auto gather = [&](PeerVRows& r, const int* e, int tok) {
; #pragma unroll
;     for (int i = 0; i < 16; ++i) r.v[i] = *(const u32x4*)(Vb + (size_t)e[i] * 128);
;     const float4* wp = (const float4*)(W + (size_t)tok * 128 + 16 * q);
; #pragma unroll
;     for (int j = 0; j < 4; ++j) r.w[j] = wp[j];
;   };
;     ...
;     float* xr = p.out + (size_t)tok * 1024 + 128 * g + 16 * s + 2 * q;
;     float2 y = *(const float2*)xr;
;     y.x += r2[0]; y.y += r2[1];
;     *(float2*)xr = y;
;     const float ss = wave_sum(y.x * y.x + y.y * y.y);
;     if (lane == 0) SSP[tok] = ss;
;   };
;   int ea[16], eb[16];
;   PeerVRows ga, gb;
;   peer_load_e(ea, EID, tokof(0), q);
;   peer_load_e(eb, EID, tokof(1), q);
;   gather(ga, ea, tokof(0));
;   for (int k = 0; k < n; k += 2) {
;     peer_load_e(ea, EID, tokof(k + 2), q);
;     gather(gb, eb, tokof(k + 1));
;     __builtin_amdgcn_sched_barrier(0);
;     compute(ga, tokof(k));
;     __builtin_amdgcn_sched_barrier(0);
;     peer_load_e(eb, EID, tokof(k + 3), q);
;     gather(ga, ea, tokof(k + 2));
;     __builtin_amdgcn_sched_barrier(0);
	v_mov_b32_e32 v244, v238
	v_mov_b32_e32 v245, v239
	v_mov_b32_dpp v244, v238 row_shl:4 row_mask:0xf bank_mask:0x5
	v_mov_b32_dpp v245, v239 row_shl:4 row_mask:0xf bank_mask:0x5
	v_mov_b32_dpp v238, v238 row_shr:4 row_mask:0xf bank_mask:0xa
	v_mov_b32_dpp v239, v239 row_shr:4 row_mask:0xf bank_mask:0xa
	v_mov_b32_dpp v124, v244 quad_perm:[0,0,0,0] row_mask:0xf bank_mask:0xf
	v_mov_b32_dpp v125, v245 quad_perm:[0,0,0,0] row_mask:0xf bank_mask:0xf
	v_mov_b32_dpp v126, v244 quad_perm:[1,1,1,1] row_mask:0xf bank_mask:0xf
	v_mov_b32_dpp v127, v245 quad_perm:[1,1,1,1] row_mask:0xf bank_mask:0xf
	v_mov_b32_dpp v72, v244 quad_perm:[2,2,2,2] row_mask:0xf bank_mask:0xf
	v_mov_b32_dpp v73, v245 quad_perm:[2,2,2,2] row_mask:0xf bank_mask:0xf
	v_mov_b32_dpp v74, v244 quad_perm:[3,3,3,3] row_mask:0xf bank_mask:0xf
	v_mov_b32_dpp v75, v245 quad_perm:[3,3,3,3] row_mask:0xf bank_mask:0xf
	v_mov_b32_dpp v180, v238 quad_perm:[0,0,0,0] row_mask:0xf bank_mask:0xf
	v_mov_b32_dpp v181, v239 quad_perm:[0,0,0,0] row_mask:0xf bank_mask:0xf
	v_mov_b32_dpp v182, v238 quad_perm:[1,1,1,1] row_mask:0xf bank_mask:0xf
	v_mov_b32_dpp v183, v239 quad_perm:[1,1,1,1] row_mask:0xf bank_mask:0xf
	v_mov_b32_dpp v156, v238 quad_perm:[2,2,2,2] row_mask:0xf bank_mask:0xf
	v_mov_b32_dpp v157, v239 quad_perm:[2,2,2,2] row_mask:0xf bank_mask:0xf
	v_mov_b32_dpp v158, v238 quad_perm:[3,3,3,3] row_mask:0xf bank_mask:0xf
	v_mov_b32_dpp v159, v239 quad_perm:[3,3,3,3] row_mask:0xf bank_mask:0xf
	v_mov_b32_e32 v244, v236
	v_mov_b32_e32 v245, v237
	v_mov_b32_dpp v244, v236 row_shl:4 row_mask:0xf bank_mask:0x5
	v_mov_b32_dpp v245, v237 row_shl:4 row_mask:0xf bank_mask:0x5
	v_mov_b32_dpp v236, v236 row_shr:4 row_mask:0xf bank_mask:0xa
	v_mov_b32_dpp v237, v237 row_shr:4 row_mask:0xf bank_mask:0xa
	v_mov_b32_dpp v176, v244 quad_perm:[0,0,0,0] row_mask:0xf bank_mask:0xf
	v_mov_b32_dpp v177, v245 quad_perm:[0,0,0,0] row_mask:0xf bank_mask:0xf
	v_mov_b32_dpp v178, v244 quad_perm:[1,1,1,1] row_mask:0xf bank_mask:0xf
	v_mov_b32_dpp v179, v245 quad_perm:[1,1,1,1] row_mask:0xf bank_mask:0xf
	v_mov_b32_dpp v172, v244 quad_perm:[2,2,2,2] row_mask:0xf bank_mask:0xf
	v_mov_b32_dpp v173, v245 quad_perm:[2,2,2,2] row_mask:0xf bank_mask:0xf
	v_mov_b32_dpp v174, v244 quad_perm:[3,3,3,3] row_mask:0xf bank_mask:0xf
	v_mov_b32_dpp v175, v245 quad_perm:[3,3,3,3] row_mask:0xf bank_mask:0xf
	v_mov_b32_dpp v188, v236 quad_perm:[0,0,0,0] row_mask:0xf bank_mask:0xf
	v_mov_b32_dpp v189, v237 quad_perm:[0,0,0,0] row_mask:0xf bank_mask:0xf
	v_mov_b32_dpp v190, v236 quad_perm:[1,1,1,1] row_mask:0xf bank_mask:0xf
	v_mov_b32_dpp v191, v237 quad_perm:[1,1,1,1] row_mask:0xf bank_mask:0xf
	v_mov_b32_dpp v184, v236 quad_perm:[2,2,2,2] row_mask:0xf bank_mask:0xf
	v_mov_b32_dpp v185, v237 quad_perm:[2,2,2,2] row_mask:0xf bank_mask:0xf
	v_mov_b32_dpp v186, v236 quad_perm:[3,3,3,3] row_mask:0xf bank_mask:0xf
	v_mov_b32_dpp v187, v237 quad_perm:[3,3,3,3] row_mask:0xf bank_mask:0xf
	v_pk_add_f32 v[2:3], v[0:1], v[34:35]
	global_store_dwordx2 v[32:33], v[2:3], off
	v_pk_mul_f32 v[0:1], v[2:3], v[2:3]
	s_nop 0
	v_add_f32_e32 v0, v0, v1
	ds_bpermute_b32 v1, v210, v0
	s_waitcnt lgkmcnt(0)
	v_add_f32_e32 v0, v0, v1
	ds_bpermute_b32 v1, v211, v0
	s_waitcnt lgkmcnt(0)
	v_add_f32_e32 v0, v0, v1
	ds_bpermute_b32 v1, v212, v0
	s_waitcnt lgkmcnt(0)
	v_add_f32_e32 v0, v0, v1
	ds_bpermute_b32 v1, v213, v0
	s_waitcnt lgkmcnt(0)
	v_add_f32_e32 v0, v0, v1
	ds_bpermute_b32 v1, v214, v0
	s_waitcnt lgkmcnt(0)
	v_add_f32_e32 v0, v0, v1
	ds_bpermute_b32 v1, v215, v0
	s_and_saveexec_b64 s[8:9], s[6:7]
	s_cbranch_execz .LBB0_1479
	s_waitcnt lgkmcnt(0)
	v_add_f32_e32 v2, v0, v1
	v_lshl_add_u64 v[0:1], v[204:205], 2, s[12:13]
	global_store_dword v[0:1], v2, off
.LBB0_1479:
	s_or_b64 exec, exec, s[8:9]
	v_min_i32_e32 v0, s1, v195
	s_waitcnt lgkmcnt(0)
	v_mad_u64_u32 v[0:1], s[8:9], v0, s18, v[194:195]
	v_ashrrev_i32_e32 v1, 31, v0
	v_lshlrev_b64 v[0:1], 9, v[0:1]
	v_lshl_add_u64 v[0:1], v[198:199], 0, v[0:1]
	v_lshl_add_u64 v[234:235], v[0:1], 0, v[232:233]
	global_load_dwordx2 v[240:241], v[234:235], off
	v_mov_b32_e32 v0, v188
	v_mov_b32_e32 v2, v189
	v_lshlrev_b32_e32 v0, 7, v0
	v_lshlrev_b32_e32 v2, 7, v2
	v_add_u32_e32 v0, v231, v0
	v_add_u32_e32 v2, v231, v2
	global_load_dwordx4 v[88:91], v0, s[100:101]
	global_load_dwordx4 v[84:87], v2, s[100:101]
	v_mov_b32_e32 v0, v190
	v_mov_b32_e32 v2, v191
	v_lshlrev_b32_e32 v0, 7, v0
	v_lshlrev_b32_e32 v2, 7, v2
	v_add_u32_e32 v0, v231, v0
	v_add_u32_e32 v2, v231, v2
	global_load_dwordx4 v[80:83], v0, s[100:101]
	global_load_dwordx4 v[76:79], v2, s[100:101]
	v_mov_b32_e32 v0, v184
	v_mov_b32_e32 v2, v185
	v_lshlrev_b32_e32 v0, 7, v0
	v_lshlrev_b32_e32 v2, 7, v2
	v_add_u32_e32 v0, v231, v0
	v_add_u32_e32 v2, v231, v2
	global_load_dwordx4 v[64:67], v0, s[100:101]
	global_load_dwordx4 v[56:59], v2, s[100:101]
	v_mov_b32_e32 v0, v186
	v_mov_b32_e32 v2, v187
	v_lshlrev_b32_e32 v0, 7, v0
	v_lshlrev_b32_e32 v2, 7, v2
	v_add_u32_e32 v0, v231, v0
	v_add_u32_e32 v2, v231, v2
	global_load_dwordx4 v[48:51], v0, s[100:101]
	global_load_dwordx4 v[44:47], v2, s[100:101]
	v_mov_b32_e32 v0, v176
	v_mov_b32_e32 v2, v177
	v_lshlrev_b32_e32 v0, 7, v0
	v_lshlrev_b32_e32 v2, 7, v2
	v_add_u32_e32 v0, v231, v0
	v_add_u32_e32 v2, v231, v2
	global_load_dwordx4 v[40:43], v0, s[100:101]
	global_load_dwordx4 v[36:39], v2, s[100:101]
	v_mov_b32_e32 v0, v178
	v_mov_b32_e32 v2, v179
	v_lshlrev_b32_e32 v0, 7, v0
	v_lshlrev_b32_e32 v2, 7, v2
	v_add_u32_e32 v0, v231, v0
	v_add_u32_e32 v2, v231, v2
	global_load_dwordx4 v[32:35], v0, s[100:101]
	global_load_dwordx4 v[24:27], v2, s[100:101]
	v_mov_b32_e32 v0, v172
	v_mov_b32_e32 v2, v173
	v_lshlrev_b32_e32 v0, 7, v0
	v_lshlrev_b32_e32 v2, 7, v2
	v_add_u32_e32 v0, v231, v0
	v_add_u32_e32 v2, v231, v2
	global_load_dwordx4 v[20:23], v0, s[100:101]
	global_load_dwordx4 v[16:19], v2, s[100:101]
	v_mov_b32_e32 v0, v174
	v_mov_b32_e32 v2, v175
	v_lshlrev_b32_e32 v0, 7, v0
	v_lshlrev_b32_e32 v2, 7, v2
	v_add_u32_e32 v0, v231, v0
	v_add_u32_e32 v2, v231, v2
	v_lshl_add_u64 v[52:53], v[200:201], 0, v[208:209]
	global_load_dwordx4 v[8:11], v0, s[100:101]
	global_load_dwordx4 v[4:7], v2, s[100:101]
	s_nop 0
	v_lshl_add_u64 v[234:235], v[52:53], 0, v[232:233]
	global_load_dwordx2 v[242:243], v[234:235], off
	s_nop 0
	v_cmp_lt_i32_e64 s[8:9], s16, v193
	s_and_saveexec_b64 s[16:17], s[8:9]
	s_cbranch_execz .LBB0_1476
; DI void peer_v_phase(const Params& p) {
;     ...
; #pragma unroll
;     for (int i = 0; i < 16; ++i) {
;       const float wi = (i & 3) == 0 ? r.w[i >> 2].x : (i & 3) == 1 ? r.w[i >> 2].y : (i & 3) == 2 ? r.w[i >> 2].z : r.w[i >> 2].w;
;       const f32x2 w2 = {wi, wi};
; #pragma unroll
;       for (int j = 0; j < 4; ++j) {
;         const f32x2 lo = __builtin_amdgcn_cvt_pk_f32_fp8((int)r.v[i][j], false);
;         const f32x2 hi = __builtin_amdgcn_cvt_pk_f32_fp8((int)r.v[i][j], true);
;         o2[2 * j] = __builtin_elementwise_fma(lo, w2, o2[2 * j]);
;         o2[2 * j + 1] = __builtin_elementwise_fma(hi, w2, o2[2 * j + 1]);
;       }
;     }
	v_cvt_pk_f32_fp8_e32 v[172:173], v168
	v_cvt_pk_f32_fp8_sdwa v[174:175], v168 src0_sel:WORD_1
	v_cvt_pk_f32_fp8_e32 v[176:177], v169
	v_cvt_pk_f32_fp8_sdwa v[168:169], v169 src0_sel:WORD_1
	v_cvt_pk_f32_fp8_e32 v[188:189], v164
	v_cvt_pk_f32_fp8_sdwa v[190:191], v164 src0_sel:WORD_1
	v_cvt_pk_f32_fp8_e32 v[208:209], v165
	v_cvt_pk_f32_fp8_sdwa v[164:165], v165 src0_sel:WORD_1
	v_pk_fma_f32 v[172:173], v[172:173], v[180:181], 0 op_sel_hi:[1,0,0]
	v_pk_fma_f32 v[174:175], v[174:175], v[180:181], 0 op_sel_hi:[1,0,0]
	v_pk_fma_f32 v[168:169], v[168:169], v[180:181], 0 op_sel_hi:[1,0,0]
	v_cvt_pk_f32_fp8_e32 v[178:179], v170
	v_cvt_pk_f32_fp8_sdwa v[184:185], v170 src0_sel:WORD_1
	v_cvt_pk_f32_fp8_e32 v[186:187], v171
	v_cvt_pk_f32_fp8_sdwa v[170:171], v171 src0_sel:WORD_1
	v_pk_fma_f32 v[172:173], v[188:189], v[180:181], v[172:173] op_sel:[0,1,0]
	v_pk_fma_f32 v[174:175], v[190:191], v[180:181], v[174:175] op_sel:[0,1,0]
	v_pk_fma_f32 v[164:165], v[164:165], v[180:181], v[168:169] op_sel:[0,1,0]
	v_cvt_pk_f32_fp8_e32 v[168:169], v166
	v_cvt_pk_f32_fp8_sdwa v[188:189], v166 src0_sel:WORD_1
	v_cvt_pk_f32_fp8_e32 v[190:191], v167
	v_cvt_pk_f32_fp8_sdwa v[166:167], v167 src0_sel:WORD_1
	v_pk_fma_f32 v[176:177], v[176:177], v[180:181], 0 op_sel_hi:[1,0,0]
	v_pk_fma_f32 v[178:179], v[178:179], v[180:181], 0 op_sel_hi:[1,0,0]
	v_pk_fma_f32 v[184:185], v[184:185], v[180:181], 0 op_sel_hi:[1,0,0]
	v_pk_fma_f32 v[186:187], v[186:187], v[180:181], 0 op_sel_hi:[1,0,0]
	v_pk_fma_f32 v[170:171], v[170:171], v[180:181], 0 op_sel_hi:[1,0,0]
	v_pk_fma_f32 v[176:177], v[208:209], v[180:181], v[176:177] op_sel:[0,1,0]
	v_pk_fma_f32 v[168:169], v[168:169], v[180:181], v[178:179] op_sel:[0,1,0]
	v_pk_fma_f32 v[178:179], v[188:189], v[180:181], v[184:185] op_sel:[0,1,0]
	v_pk_fma_f32 v[184:185], v[190:191], v[180:181], v[186:187] op_sel:[0,1,0]
	v_pk_fma_f32 v[166:167], v[166:167], v[180:181], v[170:171] op_sel:[0,1,0]
	v_cvt_pk_f32_fp8_e32 v[170:171], v160
	v_cvt_pk_f32_fp8_sdwa v[180:181], v160 src0_sel:WORD_1
	v_cvt_pk_f32_fp8_e32 v[186:187], v161
	v_cvt_pk_f32_fp8_sdwa v[160:161], v161 src0_sel:WORD_1
	v_pk_fma_f32 v[170:171], v[170:171], v[182:183], v[172:173] op_sel_hi:[1,0,1]
	v_pk_fma_f32 v[172:173], v[180:181], v[182:183], v[174:175] op_sel_hi:[1,0,1]
	v_pk_fma_f32 v[174:175], v[186:187], v[182:183], v[176:177] op_sel_hi:[1,0,1]
	v_pk_fma_f32 v[160:161], v[160:161], v[182:183], v[164:165] op_sel_hi:[1,0,1]
	v_cvt_pk_f32_fp8_e32 v[164:165], v162
	v_cvt_pk_f32_fp8_sdwa v[176:177], v162 src0_sel:WORD_1
	v_cvt_pk_f32_fp8_e32 v[180:181], v163
	v_cvt_pk_f32_fp8_sdwa v[162:163], v163 src0_sel:WORD_1
	v_pk_fma_f32 v[164:165], v[164:165], v[182:183], v[168:169] op_sel_hi:[1,0,1]
	v_pk_fma_f32 v[168:169], v[176:177], v[182:183], v[178:179] op_sel_hi:[1,0,1]
	v_pk_fma_f32 v[176:177], v[180:181], v[182:183], v[184:185] op_sel_hi:[1,0,1]
	v_pk_fma_f32 v[162:163], v[162:163], v[182:183], v[166:167] op_sel_hi:[1,0,1]
	v_mov_b32_e32 v166, v183
	v_cvt_pk_f32_fp8_e32 v[178:179], v152
	v_cvt_pk_f32_fp8_sdwa v[180:181], v152 src0_sel:WORD_1
	v_cvt_pk_f32_fp8_e32 v[182:183], v153
	v_cvt_pk_f32_fp8_sdwa v[152:153], v153 src0_sel:WORD_1
	v_pk_fma_f32 v[170:171], v[178:179], v[166:167], v[170:171] op_sel_hi:[1,0,1]
	v_pk_fma_f32 v[172:173], v[180:181], v[166:167], v[172:173] op_sel_hi:[1,0,1]
	v_cvt_pk_f32_fp8_sdwa v[178:179], v154 src0_sel:WORD_1
	v_pk_fma_f32 v[152:153], v[152:153], v[166:167], v[160:161] op_sel_hi:[1,0,1]
	v_cvt_pk_f32_fp8_e32 v[160:161], v154
	v_cvt_pk_f32_fp8_e32 v[180:181], v155
	v_cvt_pk_f32_fp8_sdwa v[154:155], v155 src0_sel:WORD_1
	v_pk_fma_f32 v[174:175], v[182:183], v[166:167], v[174:175] op_sel_hi:[1,0,1]
	v_pk_fma_f32 v[160:161], v[160:161], v[166:167], v[164:165] op_sel_hi:[1,0,1]
	v_pk_fma_f32 v[164:165], v[178:179], v[166:167], v[168:169] op_sel_hi:[1,0,1]
	v_pk_fma_f32 v[168:169], v[180:181], v[166:167], v[176:177] op_sel_hi:[1,0,1]
	v_pk_fma_f32 v[154:155], v[154:155], v[166:167], v[162:163] op_sel_hi:[1,0,1]
	v_cvt_pk_f32_fp8_e32 v[162:163], v148
	v_cvt_pk_f32_fp8_sdwa v[166:167], v148 src0_sel:WORD_1
	v_cvt_pk_f32_fp8_e32 v[176:177], v149
	v_cvt_pk_f32_fp8_sdwa v[148:149], v149 src0_sel:WORD_1
	v_pk_fma_f32 v[162:163], v[162:163], v[156:157], v[170:171] op_sel_hi:[1,0,1]
	v_pk_fma_f32 v[166:167], v[166:167], v[156:157], v[172:173] op_sel_hi:[1,0,1]
	v_pk_fma_f32 v[170:171], v[176:177], v[156:157], v[174:175] op_sel_hi:[1,0,1]
	v_pk_fma_f32 v[148:149], v[148:149], v[156:157], v[152:153] op_sel_hi:[1,0,1]
	v_cvt_pk_f32_fp8_e32 v[152:153], v150
	v_cvt_pk_f32_fp8_sdwa v[172:173], v150 src0_sel:WORD_1
	v_cvt_pk_f32_fp8_e32 v[174:175], v151
	v_cvt_pk_f32_fp8_sdwa v[150:151], v151 src0_sel:WORD_1
	v_pk_fma_f32 v[152:153], v[152:153], v[156:157], v[160:161] op_sel_hi:[1,0,1]
	v_pk_fma_f32 v[160:161], v[172:173], v[156:157], v[164:165] op_sel_hi:[1,0,1]
	v_pk_fma_f32 v[164:165], v[174:175], v[156:157], v[168:169] op_sel_hi:[1,0,1]
	v_pk_fma_f32 v[150:151], v[150:151], v[156:157], v[154:155] op_sel_hi:[1,0,1]
	v_mov_b32_e32 v154, v157
	v_cvt_pk_f32_fp8_e32 v[156:157], v144
	v_cvt_pk_f32_fp8_sdwa v[168:169], v144 src0_sel:WORD_1
	v_cvt_pk_f32_fp8_e32 v[172:173], v145
	v_cvt_pk_f32_fp8_sdwa v[144:145], v145 src0_sel:WORD_1
	v_pk_fma_f32 v[156:157], v[156:157], v[154:155], v[162:163] op_sel_hi:[1,0,1]
	v_pk_fma_f32 v[162:163], v[168:169], v[154:155], v[166:167] op_sel_hi:[1,0,1]
	v_pk_fma_f32 v[166:167], v[172:173], v[154:155], v[170:171] op_sel_hi:[1,0,1]
	v_pk_fma_f32 v[144:145], v[144:145], v[154:155], v[148:149] op_sel_hi:[1,0,1]
	v_cvt_pk_f32_fp8_e32 v[148:149], v146
	v_cvt_pk_f32_fp8_sdwa v[168:169], v146 src0_sel:WORD_1
	v_cvt_pk_f32_fp8_e32 v[170:171], v147
; DI void peer_v_phase(const Params& p) {
;     ...
; #pragma unroll
;     for (int i = 0; i < 16; ++i) {
;       const float wi = (i & 3) == 0 ? r.w[i >> 2].x : (i & 3) == 1 ? r.w[i >> 2].y : (i & 3) == 2 ? r.w[i >> 2].z : r.w[i >> 2].w;
;       const f32x2 w2 = {wi, wi};
; #pragma unroll
;       for (int j = 0; j < 4; ++j) {
;         const f32x2 lo = __builtin_amdgcn_cvt_pk_f32_fp8((int)r.v[i][j], false);
;         const f32x2 hi = __builtin_amdgcn_cvt_pk_f32_fp8((int)r.v[i][j], true);
;         o2[2 * j] = __builtin_elementwise_fma(lo, w2, o2[2 * j]);
;         o2[2 * j + 1] = __builtin_elementwise_fma(hi, w2, o2[2 * j + 1]);
;       }
;     }
	v_cvt_pk_f32_fp8_sdwa v[146:147], v147 src0_sel:WORD_1
	v_pk_fma_f32 v[148:149], v[148:149], v[154:155], v[152:153] op_sel_hi:[1,0,1]
	v_pk_fma_f32 v[152:153], v[168:169], v[154:155], v[160:161] op_sel_hi:[1,0,1]
	v_pk_fma_f32 v[160:161], v[170:171], v[154:155], v[164:165] op_sel_hi:[1,0,1]
	v_pk_fma_f32 v[146:147], v[146:147], v[154:155], v[150:151] op_sel_hi:[1,0,1]
	v_cvt_pk_f32_fp8_e32 v[150:151], v140
	v_cvt_pk_f32_fp8_sdwa v[154:155], v140 src0_sel:WORD_1
	v_cvt_pk_f32_fp8_e32 v[164:165], v141
	v_cvt_pk_f32_fp8_sdwa v[140:141], v141 src0_sel:WORD_1
	v_pk_fma_f32 v[150:151], v[150:151], v[158:159], v[156:157] op_sel_hi:[1,0,1]
	v_pk_fma_f32 v[154:155], v[154:155], v[158:159], v[162:163] op_sel_hi:[1,0,1]
	v_pk_fma_f32 v[156:157], v[164:165], v[158:159], v[166:167] op_sel_hi:[1,0,1]
	v_pk_fma_f32 v[140:141], v[140:141], v[158:159], v[144:145] op_sel_hi:[1,0,1]
	v_cvt_pk_f32_fp8_e32 v[144:145], v142
	v_cvt_pk_f32_fp8_sdwa v[162:163], v142 src0_sel:WORD_1
	v_cvt_pk_f32_fp8_e32 v[164:165], v143
	v_cvt_pk_f32_fp8_sdwa v[142:143], v143 src0_sel:WORD_1
	v_pk_fma_f32 v[144:145], v[144:145], v[158:159], v[148:149] op_sel_hi:[1,0,1]
	v_pk_fma_f32 v[148:149], v[162:163], v[158:159], v[152:153] op_sel_hi:[1,0,1]
	v_pk_fma_f32 v[152:153], v[164:165], v[158:159], v[160:161] op_sel_hi:[1,0,1]
	v_pk_fma_f32 v[142:143], v[142:143], v[158:159], v[146:147] op_sel_hi:[1,0,1]
	v_mov_b32_e32 v146, v159
	v_cvt_pk_f32_fp8_e32 v[158:159], v136
	v_cvt_pk_f32_fp8_sdwa v[160:161], v136 src0_sel:WORD_1
	v_cvt_pk_f32_fp8_e32 v[162:163], v137
	v_cvt_pk_f32_fp8_sdwa v[136:137], v137 src0_sel:WORD_1
	v_pk_fma_f32 v[150:151], v[158:159], v[146:147], v[150:151] op_sel_hi:[1,0,1]
	v_pk_fma_f32 v[154:155], v[160:161], v[146:147], v[154:155] op_sel_hi:[1,0,1]
	v_cvt_pk_f32_fp8_sdwa v[158:159], v138 src0_sel:WORD_1
	v_pk_fma_f32 v[136:137], v[136:137], v[146:147], v[140:141] op_sel_hi:[1,0,1]
	v_cvt_pk_f32_fp8_e32 v[140:141], v138
	v_cvt_pk_f32_fp8_e32 v[160:161], v139
	v_cvt_pk_f32_fp8_sdwa v[138:139], v139 src0_sel:WORD_1
	v_pk_fma_f32 v[156:157], v[162:163], v[146:147], v[156:157] op_sel_hi:[1,0,1]
	v_pk_fma_f32 v[140:141], v[140:141], v[146:147], v[144:145] op_sel_hi:[1,0,1]
	v_pk_fma_f32 v[144:145], v[158:159], v[146:147], v[148:149] op_sel_hi:[1,0,1]
	v_pk_fma_f32 v[148:149], v[160:161], v[146:147], v[152:153] op_sel_hi:[1,0,1]
	v_pk_fma_f32 v[138:139], v[138:139], v[146:147], v[142:143] op_sel_hi:[1,0,1]
	v_cvt_pk_f32_fp8_e32 v[142:143], v128
	v_cvt_pk_f32_fp8_sdwa v[146:147], v128 src0_sel:WORD_1
	v_cvt_pk_f32_fp8_e32 v[152:153], v129
	v_cvt_pk_f32_fp8_sdwa v[128:129], v129 src0_sel:WORD_1
	v_pk_fma_f32 v[142:143], v[142:143], v[124:125], v[150:151] op_sel_hi:[1,0,1]
	v_pk_fma_f32 v[146:147], v[146:147], v[124:125], v[154:155] op_sel_hi:[1,0,1]
	v_pk_fma_f32 v[150:151], v[152:153], v[124:125], v[156:157] op_sel_hi:[1,0,1]
	v_pk_fma_f32 v[128:129], v[128:129], v[124:125], v[136:137] op_sel_hi:[1,0,1]
	v_cvt_pk_f32_fp8_e32 v[136:137], v130
	v_cvt_pk_f32_fp8_sdwa v[152:153], v130 src0_sel:WORD_1
	v_cvt_pk_f32_fp8_e32 v[154:155], v131
	v_cvt_pk_f32_fp8_sdwa v[130:131], v131 src0_sel:WORD_1
	v_pk_fma_f32 v[136:137], v[136:137], v[124:125], v[140:141] op_sel_hi:[1,0,1]
	v_pk_fma_f32 v[140:141], v[152:153], v[124:125], v[144:145] op_sel_hi:[1,0,1]
	v_pk_fma_f32 v[144:145], v[154:155], v[124:125], v[148:149] op_sel_hi:[1,0,1]
	v_pk_fma_f32 v[130:131], v[130:131], v[124:125], v[138:139] op_sel_hi:[1,0,1]
	v_cvt_pk_f32_fp8_e32 v[138:139], v120
	v_cvt_pk_f32_fp8_sdwa v[148:149], v120 src0_sel:WORD_1
	v_cvt_pk_f32_fp8_e32 v[152:153], v121
	v_cvt_pk_f32_fp8_sdwa v[120:121], v121 src0_sel:WORD_1
	v_mov_b32_e32 v124, v125
	v_pk_fma_f32 v[138:139], v[138:139], v[124:125], v[142:143] op_sel_hi:[1,0,1]
	v_pk_fma_f32 v[142:143], v[148:149], v[124:125], v[146:147] op_sel_hi:[1,0,1]
	v_pk_fma_f32 v[146:147], v[152:153], v[124:125], v[150:151] op_sel_hi:[1,0,1]
	v_pk_fma_f32 v[120:121], v[120:121], v[124:125], v[128:129] op_sel_hi:[1,0,1]
	v_cvt_pk_f32_fp8_e32 v[128:129], v122
	v_cvt_pk_f32_fp8_sdwa v[148:149], v122 src0_sel:WORD_1
	v_cvt_pk_f32_fp8_e32 v[150:151], v123
	v_cvt_pk_f32_fp8_sdwa v[122:123], v123 src0_sel:WORD_1
	v_pk_fma_f32 v[128:129], v[128:129], v[124:125], v[136:137] op_sel_hi:[1,0,1]
	v_pk_fma_f32 v[136:137], v[148:149], v[124:125], v[140:141] op_sel_hi:[1,0,1]
	v_pk_fma_f32 v[140:141], v[150:151], v[124:125], v[144:145] op_sel_hi:[1,0,1]
	v_pk_fma_f32 v[122:123], v[122:123], v[124:125], v[130:131] op_sel_hi:[1,0,1]
	v_cvt_pk_f32_fp8_e32 v[124:125], v112
	v_cvt_pk_f32_fp8_sdwa v[130:131], v112 src0_sel:WORD_1
	v_cvt_pk_f32_fp8_e32 v[144:145], v113
	v_cvt_pk_f32_fp8_sdwa v[112:113], v113 src0_sel:WORD_1
	v_pk_fma_f32 v[124:125], v[124:125], v[126:127], v[138:139] op_sel_hi:[1,0,1]
	v_pk_fma_f32 v[130:131], v[130:131], v[126:127], v[142:143] op_sel_hi:[1,0,1]
	v_pk_fma_f32 v[138:139], v[144:145], v[126:127], v[146:147] op_sel_hi:[1,0,1]
	v_pk_fma_f32 v[112:113], v[112:113], v[126:127], v[120:121] op_sel_hi:[1,0,1]
	v_cvt_pk_f32_fp8_e32 v[120:121], v114
	v_cvt_pk_f32_fp8_sdwa v[142:143], v114 src0_sel:WORD_1
	v_cvt_pk_f32_fp8_e32 v[144:145], v115
	v_cvt_pk_f32_fp8_sdwa v[114:115], v115 src0_sel:WORD_1
	v_pk_fma_f32 v[120:121], v[120:121], v[126:127], v[128:129] op_sel_hi:[1,0,1]
	v_pk_fma_f32 v[128:129], v[142:143], v[126:127], v[136:137] op_sel_hi:[1,0,1]
	v_pk_fma_f32 v[136:137], v[144:145], v[126:127], v[140:141] op_sel_hi:[1,0,1]
	v_pk_fma_f32 v[114:115], v[114:115], v[126:127], v[122:123] op_sel_hi:[1,0,1]
	v_cvt_pk_f32_fp8_e32 v[122:123], v104
	v_cvt_pk_f32_fp8_sdwa v[140:141], v104 src0_sel:WORD_1
	v_cvt_pk_f32_fp8_e32 v[142:143], v105
; DI void peer_v_phase(const Params& p) {
;     ...
; #pragma unroll
;     for (int i = 0; i < 16; ++i) {
;       const float wi = (i & 3) == 0 ? r.w[i >> 2].x : (i & 3) == 1 ? r.w[i >> 2].y : (i & 3) == 2 ? r.w[i >> 2].z : r.w[i >> 2].w;
;       const f32x2 w2 = {wi, wi};
; #pragma unroll
;       for (int j = 0; j < 4; ++j) {
;         const f32x2 lo = __builtin_amdgcn_cvt_pk_f32_fp8((int)r.v[i][j], false);
;         const f32x2 hi = __builtin_amdgcn_cvt_pk_f32_fp8((int)r.v[i][j], true);
;         o2[2 * j] = __builtin_elementwise_fma(lo, w2, o2[2 * j]);
;         o2[2 * j + 1] = __builtin_elementwise_fma(hi, w2, o2[2 * j + 1]);
;       }
;     }
;     float o[16];
; #pragma unroll
;     for (int k = 0; k < 8; ++k) { o[2 * k] = o2[k][0]; o[2 * k + 1] = o2[k][1]; }
;     float r8[8], r4[4], r2[2];
; #pragma unroll
;     for (int k = 0; k < 8; ++k) {
;       const float keep = (lane & 32) ? o[k + 8] : o[k], send = (lane & 32) ? o[k] : o[k + 8];
;       r8[k] = keep + __shfl_xor(send, 32);
;     }
; #pragma unroll
;     for (int k = 0; k < 4; ++k) {
;       const float keep = (lane & 16) ? r8[k + 4] : r8[k], send = (lane & 16) ? r8[k] : r8[k + 4];
;       r4[k] = keep + __shfl_xor(send, 16);
	v_cvt_pk_f32_fp8_sdwa v[104:105], v105 src0_sel:WORD_1
	v_mov_b32_e32 v126, v127
	v_pk_fma_f32 v[122:123], v[122:123], v[126:127], v[124:125] op_sel_hi:[1,0,1]
	v_pk_fma_f32 v[124:125], v[140:141], v[126:127], v[130:131] op_sel_hi:[1,0,1]
	v_pk_fma_f32 v[130:131], v[142:143], v[126:127], v[138:139] op_sel_hi:[1,0,1]
	v_cvt_pk_f32_fp8_e32 v[138:139], v106
	v_pk_fma_f32 v[104:105], v[104:105], v[126:127], v[112:113] op_sel_hi:[1,0,1]
	v_cvt_pk_f32_fp8_sdwa v[112:113], v106 src0_sel:WORD_1
	v_cvt_pk_f32_fp8_e32 v[140:141], v107
	v_cvt_pk_f32_fp8_sdwa v[106:107], v107 src0_sel:WORD_1
	v_pk_fma_f32 v[120:121], v[138:139], v[126:127], v[120:121] op_sel_hi:[1,0,1]
	v_pk_fma_f32 v[112:113], v[112:113], v[126:127], v[128:129] op_sel_hi:[1,0,1]
	v_pk_fma_f32 v[128:129], v[140:141], v[126:127], v[136:137] op_sel_hi:[1,0,1]
	v_pk_fma_f32 v[106:107], v[106:107], v[126:127], v[114:115] op_sel_hi:[1,0,1]
	v_cvt_pk_f32_fp8_sdwa v[114:115], v100 src0_sel:WORD_1
	v_cvt_pk_f32_fp8_e32 v[126:127], v101
	v_cvt_pk_f32_fp8_e32 v[136:137], v100
	v_cvt_pk_f32_fp8_sdwa v[100:101], v101 src0_sel:WORD_1
	v_pk_fma_f32 v[114:115], v[114:115], v[72:73], v[124:125] op_sel_hi:[1,0,1]
	v_pk_fma_f32 v[124:125], v[126:127], v[72:73], v[130:131] op_sel_hi:[1,0,1]
	v_cvt_pk_f32_fp8_e32 v[126:127], v102
	v_pk_fma_f32 v[100:101], v[100:101], v[72:73], v[104:105] op_sel_hi:[1,0,1]
	v_cvt_pk_f32_fp8_sdwa v[104:105], v102 src0_sel:WORD_1
	v_cvt_pk_f32_fp8_e32 v[130:131], v103
	v_cvt_pk_f32_fp8_sdwa v[102:103], v103 src0_sel:WORD_1
	v_pk_fma_f32 v[120:121], v[126:127], v[72:73], v[120:121] op_sel_hi:[1,0,1]
	v_cvt_pk_f32_fp8_e32 v[126:127], v92
	v_pk_fma_f32 v[122:123], v[136:137], v[72:73], v[122:123] op_sel_hi:[1,0,1]
	v_pk_fma_f32 v[102:103], v[102:103], v[72:73], v[106:107] op_sel_hi:[1,0,1]
	v_cvt_pk_f32_fp8_sdwa v[106:107], v92 src0_sel:WORD_1
	v_pk_fma_f32 v[104:105], v[104:105], v[72:73], v[112:113] op_sel_hi:[1,0,1]
	v_pk_fma_f32 v[112:113], v[130:131], v[72:73], v[128:129] op_sel_hi:[1,0,1]
	v_mov_b32_e32 v72, v73
	v_pk_fma_f32 v[122:123], v[126:127], v[72:73], v[122:123] op_sel_hi:[1,0,1]
	v_cvt_pk_f32_fp8_e32 v[126:127], v93
	v_cvt_pk_f32_fp8_sdwa v[92:93], v93 src0_sel:WORD_1
	v_pk_fma_f32 v[106:107], v[106:107], v[72:73], v[114:115] op_sel_hi:[1,0,1]
	v_cvt_pk_f32_fp8_e32 v[114:115], v94
	v_pk_fma_f32 v[124:125], v[126:127], v[72:73], v[124:125] op_sel_hi:[1,0,1]
	v_pk_fma_f32 v[92:93], v[92:93], v[72:73], v[100:101] op_sel_hi:[1,0,1]
	v_cvt_pk_f32_fp8_sdwa v[100:101], v94 src0_sel:WORD_1
	v_pk_fma_f32 v[114:115], v[114:115], v[72:73], v[120:121] op_sel_hi:[1,0,1]
	v_cvt_pk_f32_fp8_e32 v[120:121], v95
	v_cvt_pk_f32_fp8_sdwa v[94:95], v95 src0_sel:WORD_1
	v_pk_fma_f32 v[100:101], v[100:101], v[72:73], v[104:105] op_sel_hi:[1,0,1]
	v_cvt_pk_f32_fp8_e32 v[104:105], v68
	v_pk_fma_f32 v[112:113], v[120:121], v[72:73], v[112:113] op_sel_hi:[1,0,1]
	v_lshlrev_b64 v[120:121], 12, v[206:207]
	v_lshl_add_u64 v[120:121], v[202:203], 0, v[120:121]
	v_pk_fma_f32 v[72:73], v[94:95], v[72:73], v[102:103] op_sel_hi:[1,0,1]
	v_pk_fma_f32 v[102:103], v[104:105], v[74:75], v[122:123] op_sel_hi:[1,0,1]
	global_load_dwordx2 v[122:123], v[120:121], off
	v_cvt_pk_f32_fp8_sdwa v[94:95], v68 src0_sel:WORD_1
	v_cvt_pk_f32_fp8_e32 v[104:105], v69
	v_cvt_pk_f32_fp8_sdwa v[68:69], v69 src0_sel:WORD_1
	v_pk_fma_f32 v[94:95], v[94:95], v[74:75], v[106:107] op_sel_hi:[1,0,1]
	v_pk_fma_f32 v[104:105], v[104:105], v[74:75], v[124:125] op_sel_hi:[1,0,1]
	v_pk_fma_f32 v[68:69], v[68:69], v[74:75], v[92:93] op_sel_hi:[1,0,1]
	v_cvt_pk_f32_fp8_e32 v[92:93], v70
	v_cvt_pk_f32_fp8_sdwa v[106:107], v70 src0_sel:WORD_1
	v_cvt_pk_f32_fp8_e32 v[124:125], v71
	v_cvt_pk_f32_fp8_sdwa v[70:71], v71 src0_sel:WORD_1
	v_pk_fma_f32 v[92:93], v[92:93], v[74:75], v[114:115] op_sel_hi:[1,0,1]
	v_pk_fma_f32 v[100:101], v[106:107], v[74:75], v[100:101] op_sel_hi:[1,0,1]
	v_pk_fma_f32 v[106:107], v[124:125], v[74:75], v[112:113] op_sel_hi:[1,0,1]
	v_pk_fma_f32 v[70:71], v[70:71], v[74:75], v[72:73] op_sel_hi:[1,0,1]
	v_mov_b32_e32 v72, v75
	v_cvt_pk_f32_fp8_e32 v[74:75], v60
	v_cvt_pk_f32_fp8_sdwa v[112:113], v60 src0_sel:WORD_1
	v_cvt_pk_f32_fp8_e32 v[114:115], v61
	v_cvt_pk_f32_fp8_sdwa v[60:61], v61 src0_sel:WORD_1
	v_pk_fma_f32 v[74:75], v[74:75], v[72:73], v[102:103] op_sel_hi:[1,0,1]
	v_pk_fma_f32 v[94:95], v[112:113], v[72:73], v[94:95] op_sel_hi:[1,0,1]
	v_pk_fma_f32 v[102:103], v[114:115], v[72:73], v[104:105] op_sel_hi:[1,0,1]
	v_pk_fma_f32 v[60:61], v[60:61], v[72:73], v[68:69] op_sel_hi:[1,0,1]
	v_cvt_pk_f32_fp8_e32 v[68:69], v62
	v_cvt_pk_f32_fp8_sdwa v[104:105], v62 src0_sel:WORD_1
	v_cvt_pk_f32_fp8_e32 v[112:113], v63
	v_cvt_pk_f32_fp8_sdwa v[62:63], v63 src0_sel:WORD_1
	v_pk_fma_f32 v[68:69], v[68:69], v[72:73], v[92:93] op_sel_hi:[1,0,1]
	v_pk_fma_f32 v[92:93], v[104:105], v[72:73], v[100:101] op_sel_hi:[1,0,1]
	v_pk_fma_f32 v[100:101], v[112:113], v[72:73], v[106:107] op_sel_hi:[1,0,1]
	v_pk_fma_f32 v[62:63], v[62:63], v[72:73], v[70:71] op_sel_hi:[1,0,1]
	v_cndmask_b32_e32 v70, v74, v68, vcc
	v_cndmask_b32_e32 v71, v75, v69, vcc
	ds_bpermute_b32 v70, v210, v70
	ds_bpermute_b32 v71, v210, v71
	v_cndmask_b32_e32 v72, v94, v92, vcc
	v_cndmask_b32_e32 v73, v95, v93, vcc
	ds_bpermute_b32 v72, v210, v72
	ds_bpermute_b32 v73, v210, v73
	v_cndmask_b32_e32 v104, v102, v100, vcc
	v_cndmask_b32_e32 v105, v103, v101, vcc
	v_cndmask_b32_e32 v106, v60, v62, vcc
	v_cndmask_b32_e32 v107, v61, v63, vcc
	ds_bpermute_b32 v104, v210, v104
	ds_bpermute_b32 v105, v210, v105
	ds_bpermute_b32 v106, v210, v106
	ds_bpermute_b32 v107, v210, v107
	v_cndmask_b32_e32 v69, v69, v75, vcc
	v_cndmask_b32_e32 v68, v68, v74, vcc
	s_waitcnt lgkmcnt(6)
; DI void peer_v_phase(const Params& p) {
;     ...
;     float r8[8], r4[4], r2[2];
; #pragma unroll
;     for (int k = 0; k < 8; ++k) {
;       const float keep = (lane & 32) ? o[k + 8] : o[k], send = (lane & 32) ? o[k] : o[k + 8];
;       r8[k] = keep + __shfl_xor(send, 32);
;     }
; #pragma unroll
;     for (int k = 0; k < 4; ++k) {
;       const float keep = (lane & 16) ? r8[k + 4] : r8[k], send = (lane & 16) ? r8[k] : r8[k + 4];
;       r4[k] = keep + __shfl_xor(send, 16);
;     }
; #pragma unroll
;     for (int k = 0; k < 2; ++k) {
;       const float keep = (lane & 8) ? r4[k + 2] : r4[k], send = (lane & 8) ? r4[k] : r4[k + 2];
;       r2[k] = keep + __shfl_xor(send, 8);
;     }
;     float* xr = p.out + (size_t)tok * 1024 + 128 * g + 16 * s + 2 * q;
;     float2 y = *(const float2*)xr;
;     y.x += r2[0]; y.y += r2[1];
;     *(float2*)xr = y;
;     const float ss = wave_sum(y.x * y.x + y.y * y.y);
;     if (lane == 0) SSP[tok] = ss;
	v_pk_add_f32 v[68:69], v[68:69], v[70:71]
	v_cndmask_b32_e32 v71, v93, v95, vcc
	v_cndmask_b32_e32 v70, v92, v94, vcc
	s_waitcnt lgkmcnt(4)
	v_pk_add_f32 v[70:71], v[70:71], v[72:73]
	v_cndmask_b32_e32 v73, v101, v103, vcc
	v_cndmask_b32_e32 v72, v100, v102, vcc
	v_cndmask_b32_e32 v61, v63, v61, vcc
	v_cndmask_b32_e32 v60, v62, v60, vcc
	s_waitcnt lgkmcnt(2)
	v_pk_add_f32 v[72:73], v[72:73], v[104:105]
	s_waitcnt lgkmcnt(0)
	v_pk_add_f32 v[60:61], v[60:61], v[106:107]
	v_cndmask_b32_e64 v75, v73, v69, s[2:3]
	v_cndmask_b32_e64 v63, v69, v73, s[2:3]
	v_cndmask_b32_e64 v69, v70, v60, s[2:3]
	v_cndmask_b32_e64 v62, v68, v72, s[2:3]
	ds_bpermute_b32 v92, v211, v69
	v_cndmask_b32_e64 v69, v71, v61, s[2:3]
	ds_bpermute_b32 v62, v211, v62
	ds_bpermute_b32 v63, v211, v63
	ds_bpermute_b32 v93, v211, v69
	v_cndmask_b32_e64 v74, v72, v68, s[2:3]
	v_cndmask_b32_e64 v61, v61, v71, s[2:3]
	v_cndmask_b32_e64 v60, v60, v70, s[2:3]
	s_waitcnt lgkmcnt(1)
	v_pk_add_f32 v[62:63], v[74:75], v[62:63]
	s_waitcnt lgkmcnt(0)
	v_pk_add_f32 v[60:61], v[60:61], v[92:93]
	s_nop 0
	v_cndmask_b32_e64 v68, v62, v60, s[4:5]
	v_cndmask_b32_e64 v69, v63, v61, s[4:5]
	ds_bpermute_b32 v68, v212, v68
	ds_bpermute_b32 v69, v212, v69
	v_cndmask_b32_e64 v61, v61, v63, s[4:5]
	v_cndmask_b32_e64 v60, v60, v62, s[4:5]
	s_waitcnt lgkmcnt(0)
	v_pk_add_f32 v[60:61], v[60:61], v[68:69]
	s_waitcnt vmcnt(0)
	v_pk_add_f32 v[62:63], v[60:61], v[122:123]
	global_store_dwordx2 v[120:121], v[62:63], off
	v_pk_mul_f32 v[60:61], v[62:63], v[62:63]
	s_nop 0
	v_add_f32_e32 v60, v60, v61
	ds_bpermute_b32 v61, v210, v60
	s_waitcnt lgkmcnt(0)
	v_add_f32_e32 v60, v60, v61
	ds_bpermute_b32 v61, v211, v60
	s_waitcnt lgkmcnt(0)
	v_add_f32_e32 v60, v60, v61
	ds_bpermute_b32 v61, v212, v60
	s_waitcnt lgkmcnt(0)
	v_add_f32_e32 v60, v60, v61
	ds_bpermute_b32 v61, v213, v60
	s_waitcnt lgkmcnt(0)
	v_add_f32_e32 v60, v60, v61
	ds_bpermute_b32 v61, v214, v60
	s_waitcnt lgkmcnt(0)
	v_add_f32_e32 v60, v60, v61
	ds_bpermute_b32 v61, v215, v60
	s_and_b64 exec, exec, s[6:7]
	s_cbranch_execz .LBB0_1476
	s_waitcnt lgkmcnt(0)
	v_add_f32_e32 v62, v60, v61
	v_lshl_add_u64 v[60:61], v[206:207], 2, s[12:13]
	global_store_dword v[60:61], v62, off
	s_branch .LBB0_1476
